# v54 + in-proj bias loads hoisted from the epilogue start to the K-loop preheader (v0-v7 are dead inside the loop)
# baseline (speedup 1.0000x reference)
; template <class Epi>
; __device__ __forceinline__ void gemm_phase(LAS unsigned char* lds, const Gemm g, const StaticOrder& S, const Epi& E, const int tid) {
;     ...
;     for (;;) {
;         const bool has_next = S.next(ui + 1, nxt);
;         const char* nA = has_next ? (const char*)g.A + (size_t)nxt.pm * tstepA : cA; const char* nB = has_next ? (const char*)g.Bt + (size_t)nxt.pn * tstepB : cB;
;     ...
; #pragma unroll
;         for (int a = 0; a < 2; ++a)
; #pragma unroll
;             for (int b = 0; b < 2; ++b)
; #pragma unroll
;                 for (int m = 0; m < 4; ++m)
; #pragma unroll
;                     for (int n = 0; n < 2; ++n) acc[a][b][m][n] = (f32x4){0.f, 0.f, 0.f, 0.f};
;         cur = nxt; cA = nA; cB = nB; ++ui;
.LBB0_267:
	s_ashr_i32 s87, s86, 31
	s_lshl_b64 s[8:9], s[86:87], 19
	s_add_u32 s88, s6, s8
	s_addc_u32 s89, s7, s9
	s_and_b64 s[8:9], s[42:43], exec
	s_cselect_b32 s33, s89, s41
	s_cselect_b32 s36, s88, s40
	s_ashr_i32 s85, s84, 31
	s_lshl_b64 s[8:9], s[84:85], 19
	s_add_u32 s90, s23, s8
	s_addc_u32 s91, s80, s9
	s_and_b64 s[8:9], s[42:43], exec
	s_cselect_b32 s37, s91, s95
	s_cselect_b32 s45, s90, s94
	s_add_u32 s40, s40, 0x40080
	s_addc_u32 s41, s41, 0
	s_add_u32 s46, s94, 0x100
	v_mov_b32_e32 v8, 0
	s_addc_u32 s57, s95, 0
	s_mov_b32 s85, -2
	v_mov_b32_e32 v9, v8
	v_mov_b32_e32 v10, v8
	v_mov_b32_e32 v11, v8
	v_mov_b32_e32 v12, v8
	v_mov_b32_e32 v13, v8
	v_mov_b32_e32 v14, v8
	v_mov_b32_e32 v15, v8
	v_mov_b32_e32 v24, v8
	v_mov_b32_e32 v25, v8
	v_mov_b32_e32 v26, v8
	v_mov_b32_e32 v27, v8
	v_mov_b32_e32 v28, v8
	v_mov_b32_e32 v29, v8
	v_mov_b32_e32 v30, v8
	v_mov_b32_e32 v31, v8
	v_mov_b32_e32 v40, v8
	v_mov_b32_e32 v41, v8
	v_mov_b32_e32 v42, v8
	v_mov_b32_e32 v43, v8
	v_mov_b32_e32 v44, v8
	v_mov_b32_e32 v45, v8
	v_mov_b32_e32 v46, v8
	v_mov_b32_e32 v47, v8
	v_mov_b32_e32 v56, v8
	v_mov_b32_e32 v57, v8
	v_mov_b32_e32 v58, v8
	v_mov_b32_e32 v59, v8
	v_mov_b32_e32 v60, v8
	v_mov_b32_e32 v61, v8
	v_mov_b32_e32 v62, v8
	v_mov_b32_e32 v63, v8
	v_mov_b32_e32 v16, v8
	v_mov_b32_e32 v17, v8
	v_mov_b32_e32 v18, v8
	v_mov_b32_e32 v19, v8
	v_mov_b32_e32 v20, v8
	v_mov_b32_e32 v21, v8
	v_mov_b32_e32 v22, v8
	v_mov_b32_e32 v23, v8
	v_mov_b32_e32 v32, v8
	v_mov_b32_e32 v33, v8
	v_mov_b32_e32 v34, v8
	v_mov_b32_e32 v35, v8
	v_mov_b32_e32 v36, v8
	v_mov_b32_e32 v37, v8
	v_mov_b32_e32 v38, v8
	v_mov_b32_e32 v39, v8
	v_mov_b32_e32 v48, v8
	v_mov_b32_e32 v49, v8
	v_mov_b32_e32 v50, v8
	v_mov_b32_e32 v51, v8
	v_mov_b32_e32 v52, v8
	v_mov_b32_e32 v53, v8
	v_mov_b32_e32 v54, v8
	v_mov_b32_e32 v55, v8
	v_mov_b32_e32 v64, v8
	v_mov_b32_e32 v65, v8
	v_mov_b32_e32 v66, v8
	v_mov_b32_e32 v67, v8
	v_mov_b32_e32 v68, v8
	v_mov_b32_e32 v69, v8
	v_mov_b32_e32 v70, v8
	v_mov_b32_e32 v71, v8
	v_mov_b32_e32 v72, v8
	v_mov_b32_e32 v73, v8
	v_mov_b32_e32 v74, v8
	v_mov_b32_e32 v75, v8
	v_mov_b32_e32 v76, v8
	v_mov_b32_e32 v77, v8
	v_mov_b32_e32 v78, v8
	v_mov_b32_e32 v79, v8
	v_mov_b32_e32 v88, v8
	v_mov_b32_e32 v89, v8
	v_mov_b32_e32 v90, v8
	v_mov_b32_e32 v91, v8
	v_mov_b32_e32 v92, v8
	v_mov_b32_e32 v93, v8
	v_mov_b32_e32 v94, v8
	v_mov_b32_e32 v95, v8
	v_mov_b32_e32 v104, v8
	v_mov_b32_e32 v105, v8
	v_mov_b32_e32 v106, v8
	v_mov_b32_e32 v107, v8
	v_mov_b32_e32 v108, v8
	v_mov_b32_e32 v109, v8
	v_mov_b32_e32 v110, v8
	v_mov_b32_e32 v111, v8
	v_mov_b32_e32 v122, v8
	v_mov_b32_e32 v123, v8
	v_mov_b32_e32 v124, v8
	v_mov_b32_e32 v125, v8
	v_mov_b32_e32 v126, v8
	v_mov_b32_e32 v127, v8
	v_mov_b32_e32 v128, v8
	v_mov_b32_e32 v129, v8
	v_mov_b32_e32 v80, v8
	v_mov_b32_e32 v81, v8
	v_mov_b32_e32 v82, v8
	v_mov_b32_e32 v83, v8
	v_mov_b32_e32 v84, v8
	v_mov_b32_e32 v85, v8
	v_mov_b32_e32 v86, v8
	v_mov_b32_e32 v87, v8
	v_mov_b32_e32 v96, v8
	v_mov_b32_e32 v97, v8
	v_mov_b32_e32 v98, v8
	v_mov_b32_e32 v99, v8
	v_mov_b32_e32 v100, v8
	v_mov_b32_e32 v101, v8
	v_mov_b32_e32 v102, v8
	v_mov_b32_e32 v103, v8
	v_mov_b32_e32 v114, v8
	v_mov_b32_e32 v115, v8
	v_mov_b32_e32 v116, v8
	v_mov_b32_e32 v117, v8
	v_mov_b32_e32 v118, v8
	v_mov_b32_e32 v119, v8
	v_mov_b32_e32 v120, v8
	v_mov_b32_e32 v121, v8
	v_mov_b32_e32 v130, v8
	v_mov_b32_e32 v131, v8
	v_mov_b32_e32 v132, v8
	v_mov_b32_e32 v133, v8
	v_mov_b32_e32 v134, v8
	v_mov_b32_e32 v135, v8
	v_mov_b32_e32 v136, v8
	v_mov_b32_e32 v137, v8
	s_and_b64 s[8:9], exec, s[42:43]
	s_cbranch_scc0 .Lbias_skip_o
	s_lshl_b64 s[8:9], s[86:87], 14
	v_lshl_add_u64 v[4:5], v[144:145], 0, s[8:9]
	global_load_dwordx4 v[0:3], v[4:5], off offset:16
	s_nop 0
	global_load_dwordx4 v[4:7], v[4:5], off
.Lbias_skip_o:
.LBB0_268:
	s_add_u32 s8, s40, 0xfffc0080
	s_addc_u32 s9, s41, -1
	s_add_i32 s13, 0, 0x10000
	v_add_u32_e32 v162, s13, v167
	ds_read_b128 v[150:153], v162
	ds_read_b128 v[154:157], v162 offset:1024
	ds_read_b128 v[158:161], v162 offset:2048
	ds_read_b128 v[170:173], v162 offset:3072
	v_add_u32_e32 v162, s15, v167
	ds_read_b128 v[174:177], v162
	ds_read_b128 v[178:181], v162 offset:1024
	ds_read_b128 v[182:185], v162 offset:2048
	ds_read_b128 v[186:189], v162 offset:3072
	s_cmp_eq_u32 s85, 12
	s_cselect_b32 vcc_hi, s33, s9
	s_cselect_b32 vcc_lo, s36, s8
	s_cselect_b32 s95, s37, s57
	s_cselect_b32 s94, s45, s46
	s_nop 0
	s_add_i32 m0, s11, 0xc000
	ds_read_b128 v[190:193], v169
	ds_read_b128 v[200:203], v169 offset:1024
	ds_read_b128 v[204:207], v169 offset:2048
	ds_read_b128 v[208:211], v169 offset:3072
	ds_read_b128 v[212:215], v169 offset:4096
	ds_read_b128 v[234:237], v169 offset:5120
	ds_read_b128 v[238:241], v169 offset:6144
	ds_read_b128 v[242:245], v169 offset:7168
	global_load_lds_dwordx4 v146, s[40:41]
	s_nop 0
	s_add_i32 m0, s11, 0xe000
	s_nop 0
	global_load_lds_dwordx4 v148, s[40:41]
	s_waitcnt vmcnt(8)
	s_waitcnt lgkmcnt(0)
	s_barrier
; #define PG8_STAGE(bufoff, gbase, voff) do { _Pragma("unroll") for (int _i = 0; _i < 2; ++_i) \
;         __builtin_amdgcn_global_load_lds((const unsigned*)((const char*)(gbase) + (voff)[_i]), (LAS unsigned*)(lds + (bufoff) + ldsw + _i * 8192), 16, 0, 0); } while (0)
; #define PG8_LDA(dst, b, h) do { _Pragma("unroll") for (int m = 0; m < 4; ++m) _Pragma("unroll") for (int k = 0; k < 2; ++k) dst[m][k] = *(const LAS bf16x8*)(lds + PG8_SA(b, h) + aoff + m * 2048 + k * 1024); } while (0)
; #define PG8_LDB(dst, b, h) do { _Pragma("unroll") for (int n = 0; n < 2; ++n) _Pragma("unroll") for (int k = 0; k < 2; ++k) dst[n][k] = *(const LAS bf16x8*)(lds + PG8_SB(b, h) + boff + n * 2048 + k * 1024); } while (0)
; #define PG8_MMA(ai, bj, At, Bt) do { __builtin_amdgcn_s_setprio(1); _Pragma("unroll") for (int m = 0; m < 4; ++m) _Pragma("unroll") for (int n = 0; n < 2; ++n) _Pragma("unroll") for (int k = 0; k < 2; ++k) \
;         acc[ai][bj][m][n] = __builtin_amdgcn_mfma_f32_16x16x32_bf16(Bt[n][k], At[m][k], acc[ai][bj][m][n], 0, 0, 0); __builtin_amdgcn_s_setprio(0); } while (0)
; #define PG8_WAIT_V(n) asm volatile("s_waitcnt vmcnt(" #n ")" ::: "memory")
; #define PG8_WAIT_L(n) asm volatile("s_waitcnt lgkmcnt(" #n ")" ::: "memory")
; #define PG8_BAR __builtin_amdgcn_s_barrier()
; #define PG8_SCHED __builtin_amdgcn_sched_barrier(0)
; template <class Epi>
; __device__ __forceinline__ void gemm_phase(LAS unsigned char* lds, const Gemm g, const StaticOrder& S, const Epi& E, const int tid) {
;     ...
;             PG8_LDB(B0, 0, 0); PG8_LDB(B1, 0, 1); PG8_SCHED; PG8_LDA(At, 0, 0); PG8_STAGE(PG8_SA(1, 1), a1 + hstepA, voffA);
;             PG8_WAIT_V(8); PG8_WAIT_L(0); PG8_BAR; PG8_MMA(0, 0, At, B0); PG8_MMA(0, 1, At, B1); PG8_BAR; PG8_SCHED;
;             PG8_LDA(At, 0, 1); PG8_STAGE(PG8_SB(0, 0), b2, voffB); PG8_STAGE(PG8_SB(0, 1), b2 + hstepB, voffB); PG8_STAGE(PG8_SA(0, 0), a2, voffA);
;             PG8_WAIT_V(8); PG8_WAIT_L(0); PG8_BAR; PG8_MMA(1, 0, At, B0); PG8_MMA(1, 1, At, B1); PG8_BAR; PG8_SCHED;
	s_setprio 1
	s_waitcnt lgkmcnt(0)
	v_mfma_f32_16x16x32_bf16 v[134:137], v[150:153], v[190:193], v[134:137]
	v_mfma_f32_16x16x32_bf16 v[130:133], v[158:161], v[190:193], v[130:133]
	v_mfma_f32_16x16x32_bf16 v[118:121], v[150:153], v[204:207], v[118:121]
	v_mfma_f32_16x16x32_bf16 v[114:117], v[158:161], v[204:207], v[114:117]
	v_mfma_f32_16x16x32_bf16 v[100:103], v[150:153], v[212:215], v[100:103]
	v_mfma_f32_16x16x32_bf16 v[96:99], v[158:161], v[212:215], v[96:99]
	v_mfma_f32_16x16x32_bf16 v[84:87], v[150:153], v[238:241], v[84:87]
	v_mfma_f32_16x16x32_bf16 v[80:83], v[158:161], v[238:241], v[80:83]
	v_mfma_f32_16x16x32_bf16 v[134:137], v[154:157], v[200:203], v[134:137]
	v_mfma_f32_16x16x32_bf16 v[130:133], v[170:173], v[200:203], v[130:133]
	v_mfma_f32_16x16x32_bf16 v[118:121], v[154:157], v[208:211], v[118:121]
	v_mfma_f32_16x16x32_bf16 v[114:117], v[170:173], v[208:211], v[114:117]
	v_mfma_f32_16x16x32_bf16 v[100:103], v[154:157], v[234:237], v[100:103]
	v_mfma_f32_16x16x32_bf16 v[96:99], v[170:173], v[234:237], v[96:99]
	v_mfma_f32_16x16x32_bf16 v[84:87], v[154:157], v[242:245], v[84:87]
	v_mfma_f32_16x16x32_bf16 v[80:83], v[170:173], v[242:245], v[80:83]
	v_mfma_f32_16x16x32_bf16 v[126:129], v[174:177], v[190:193], v[126:129]
	v_mfma_f32_16x16x32_bf16 v[122:125], v[182:185], v[190:193], v[122:125]
	v_mfma_f32_16x16x32_bf16 v[108:111], v[174:177], v[204:207], v[108:111]
	v_mfma_f32_16x16x32_bf16 v[104:107], v[182:185], v[204:207], v[104:107]
	v_mfma_f32_16x16x32_bf16 v[92:95], v[174:177], v[212:215], v[92:95]
	v_mfma_f32_16x16x32_bf16 v[88:91], v[182:185], v[212:215], v[88:91]
	v_mfma_f32_16x16x32_bf16 v[76:79], v[174:177], v[238:241], v[76:79]
	v_mfma_f32_16x16x32_bf16 v[72:75], v[182:185], v[238:241], v[72:75]
	v_mfma_f32_16x16x32_bf16 v[126:129], v[178:181], v[200:203], v[126:129]
	v_mfma_f32_16x16x32_bf16 v[122:125], v[186:189], v[200:203], v[122:125]
	v_mfma_f32_16x16x32_bf16 v[108:111], v[178:181], v[208:211], v[108:111]
	v_mfma_f32_16x16x32_bf16 v[104:107], v[186:189], v[208:211], v[104:107]
	v_mfma_f32_16x16x32_bf16 v[92:95], v[178:181], v[234:237], v[92:95]
	v_mfma_f32_16x16x32_bf16 v[88:91], v[186:189], v[234:237], v[88:91]
	v_mfma_f32_16x16x32_bf16 v[76:79], v[178:181], v[242:245], v[76:79]
	v_mfma_f32_16x16x32_bf16 v[72:75], v[186:189], v[242:245], v[72:75]
	s_setprio 0
	s_barrier
	s_add_i32 s8, s13, s81
	s_nop 0
	s_mov_b32 m0, s8
	ds_read_b128 v[190:193], v169 offset:16384
	ds_read_b128 v[200:203], v169 offset:17408
	ds_read_b128 v[204:207], v169 offset:18432
	ds_read_b128 v[208:211], v169 offset:19456
	ds_read_b128 v[212:215], v169 offset:20480
	ds_read_b128 v[234:237], v169 offset:21504
	ds_read_b128 v[238:241], v169 offset:22528
	ds_read_b128 v[242:245], v169 offset:23552
	global_load_lds_dwordx4 v112, s[94:95]
	s_add_i32 m0, s8, 0x2000
	s_add_u32 s8, s94, 0x40000
	v_lshl_add_u64 v[228:229], s[94:95], 0, v[142:143]
	s_addc_u32 s9, s95, 0
	s_add_i32 s13, s15, s81
	global_load_lds_dwordx4 v142, s[94:95]
	s_nop 0
	s_mov_b32 m0, s13
	s_nop 0
	global_load_lds_dwordx4 v112, s[8:9]
	s_nop 0
	s_add_i32 m0, s13, 0x2000
	s_nop 0
	global_load_lds_dwordx4 v142, s[8:9]
	s_nop 0
	s_mov_b32 m0, s11
	s_nop 0
	global_load_lds_dwordx4 v138, vcc
	s_mov_b32 m0, s19
	s_nop 0
	global_load_lds_dwordx4 v140, vcc
	s_waitcnt vmcnt(8)
	s_waitcnt lgkmcnt(0)
	s_barrier
	s_setprio 1
	s_waitcnt lgkmcnt(0)
	v_mfma_f32_16x16x32_bf16 v[68:71], v[150:153], v[190:193], v[68:71]
	v_mfma_f32_16x16x32_bf16 v[64:67], v[158:161], v[190:193], v[64:67]
	v_mfma_f32_16x16x32_bf16 v[52:55], v[150:153], v[204:207], v[52:55]
	v_mfma_f32_16x16x32_bf16 v[48:51], v[158:161], v[204:207], v[48:51]
	v_mfma_f32_16x16x32_bf16 v[36:39], v[150:153], v[212:215], v[36:39]
	v_mfma_f32_16x16x32_bf16 v[32:35], v[158:161], v[212:215], v[32:35]
	v_mfma_f32_16x16x32_bf16 v[20:23], v[150:153], v[238:241], v[20:23]
	v_mfma_f32_16x16x32_bf16 v[16:19], v[158:161], v[238:241], v[16:19]
	v_mfma_f32_16x16x32_bf16 v[68:71], v[154:157], v[200:203], v[68:71]
	v_mfma_f32_16x16x32_bf16 v[64:67], v[170:173], v[200:203], v[64:67]
	v_mfma_f32_16x16x32_bf16 v[52:55], v[154:157], v[208:211], v[52:55]
	v_mfma_f32_16x16x32_bf16 v[48:51], v[170:173], v[208:211], v[48:51]
	v_mfma_f32_16x16x32_bf16 v[36:39], v[154:157], v[234:237], v[36:39]
	v_mfma_f32_16x16x32_bf16 v[32:35], v[170:173], v[234:237], v[32:35]
	v_mfma_f32_16x16x32_bf16 v[20:23], v[154:157], v[242:245], v[20:23]
	v_mfma_f32_16x16x32_bf16 v[16:19], v[170:173], v[242:245], v[16:19]
	v_mfma_f32_16x16x32_bf16 v[60:63], v[174:177], v[190:193], v[60:63]
	v_mfma_f32_16x16x32_bf16 v[56:59], v[182:185], v[190:193], v[56:59]
	v_mfma_f32_16x16x32_bf16 v[44:47], v[174:177], v[204:207], v[44:47]
	v_mfma_f32_16x16x32_bf16 v[40:43], v[182:185], v[204:207], v[40:43]
	v_mfma_f32_16x16x32_bf16 v[28:31], v[174:177], v[212:215], v[28:31]
	v_mfma_f32_16x16x32_bf16 v[24:27], v[182:185], v[212:215], v[24:27]
	v_mfma_f32_16x16x32_bf16 v[12:15], v[174:177], v[238:241], v[12:15]
	v_mfma_f32_16x16x32_bf16 v[8:11], v[182:185], v[238:241], v[8:11]
	v_mfma_f32_16x16x32_bf16 v[60:63], v[178:181], v[200:203], v[60:63]
	v_mfma_f32_16x16x32_bf16 v[56:59], v[186:189], v[200:203], v[56:59]
	v_mfma_f32_16x16x32_bf16 v[44:47], v[178:181], v[208:211], v[44:47]
	v_mfma_f32_16x16x32_bf16 v[40:43], v[186:189], v[208:211], v[40:43]
	v_mfma_f32_16x16x32_bf16 v[28:31], v[178:181], v[234:237], v[28:31]
	v_mfma_f32_16x16x32_bf16 v[24:27], v[186:189], v[234:237], v[24:27]
	v_mfma_f32_16x16x32_bf16 v[12:15], v[178:181], v[242:245], v[12:15]
	v_mfma_f32_16x16x32_bf16 v[8:11], v[186:189], v[242:245], v[8:11]
	s_setprio 0
	s_barrier
; #define PG8_STAGE(bufoff, gbase, voff) do { _Pragma("unroll") for (int _i = 0; _i < 2; ++_i) \
;         __builtin_amdgcn_global_load_lds((const unsigned*)((const char*)(gbase) + (voff)[_i]), (LAS unsigned*)(lds + (bufoff) + ldsw + _i * 8192), 16, 0, 0); } while (0)
; #define PG8_LDA(dst, b, h) do { _Pragma("unroll") for (int m = 0; m < 4; ++m) _Pragma("unroll") for (int k = 0; k < 2; ++k) dst[m][k] = *(const LAS bf16x8*)(lds + PG8_SA(b, h) + aoff + m * 2048 + k * 1024); } while (0)
; #define PG8_LDB(dst, b, h) do { _Pragma("unroll") for (int n = 0; n < 2; ++n) _Pragma("unroll") for (int k = 0; k < 2; ++k) dst[n][k] = *(const LAS bf16x8*)(lds + PG8_SB(b, h) + boff + n * 2048 + k * 1024); } while (0)
; #define PG8_MMA(ai, bj, At, Bt) do { __builtin_amdgcn_s_setprio(1); _Pragma("unroll") for (int m = 0; m < 4; ++m) _Pragma("unroll") for (int n = 0; n < 2; ++n) _Pragma("unroll") for (int k = 0; k < 2; ++k) \
;         acc[ai][bj][m][n] = __builtin_amdgcn_mfma_f32_16x16x32_bf16(Bt[n][k], At[m][k], acc[ai][bj][m][n], 0, 0, 0); __builtin_amdgcn_s_setprio(0); } while (0)
; #define PG8_WAIT_V(n) asm volatile("s_waitcnt vmcnt(" #n ")" ::: "memory")
; #define PG8_WAIT_L(n) asm volatile("s_waitcnt lgkmcnt(" #n ")" ::: "memory")
; #define PG8_BAR __builtin_amdgcn_s_barrier()
; #define PG8_SCHED __builtin_amdgcn_sched_barrier(0)
; template <class Epi>
; __device__ __forceinline__ void gemm_phase(LAS unsigned char* lds, const Gemm g, const StaticOrder& S, const Epi& E, const int tid) {
;     ...
;             PG8_LDB(B0, 1, 0); PG8_LDB(B1, 1, 1); PG8_SCHED; PG8_LDA(At, 1, 0); PG8_STAGE(PG8_SA(0, 1), a2 + hstepA, voffA);
;             PG8_WAIT_V(8); PG8_WAIT_L(0); PG8_BAR; PG8_MMA(0, 0, At, B0); PG8_MMA(0, 1, At, B1); PG8_BAR; PG8_SCHED;
;             PG8_LDA(At, 1, 1); PG8_STAGE(PG8_SB(1, 0), b3, voffB); PG8_STAGE(PG8_SB(1, 1), b3 + hstepB, voffB); PG8_STAGE(PG8_SA(1, 0), a3, voffA);
;             PG8_WAIT_V(8); PG8_WAIT_L(0); PG8_BAR; PG8_MMA(1, 0, At, B0); PG8_MMA(1, 1, At, B1); PG8_BAR; PG8_SCHED;
	s_add_i32 s13, 0, 0x18000
	s_add_i32 s31, 0, 0x1c000
	v_add_u32_e32 v170, s13, v167
	v_add_u32_e32 v186, s31, v167
	ds_read_b128 v[150:153], v170
	ds_read_b128 v[154:157], v170 offset:1024
	ds_read_b128 v[158:161], v170 offset:2048
	ds_read_b128 v[170:173], v170 offset:3072
	ds_read_b128 v[174:177], v186
	ds_read_b128 v[178:181], v186 offset:1024
	ds_read_b128 v[182:185], v186 offset:2048
	ds_read_b128 v[186:189], v186 offset:3072
	s_add_u32 s8, vcc_lo, 0x40000
	s_addc_u32 s9, vcc_hi, 0
	s_mov_b32 m0, s98
	s_nop 0
	ds_read_b128 v[190:193], v169 offset:32768
	ds_read_b128 v[200:203], v169 offset:33792
	ds_read_b128 v[204:207], v169 offset:34816
	ds_read_b128 v[208:211], v169 offset:35840
	ds_read_b128 v[212:215], v169 offset:36864
	ds_read_b128 v[234:237], v169 offset:37888
	ds_read_b128 v[238:241], v169 offset:38912
	ds_read_b128 v[242:245], v169 offset:39936
	global_load_lds_dwordx4 v138, s[8:9]
	s_nop 0
	s_mov_b32 m0, s99
	s_nop 0
	global_load_lds_dwordx4 v140, s[8:9]
	s_waitcnt vmcnt(8)
	s_waitcnt lgkmcnt(0)
	s_barrier
	s_setprio 1
	s_waitcnt lgkmcnt(0)
	v_mfma_f32_16x16x32_bf16 v[134:137], v[150:153], v[190:193], v[134:137]
	v_mfma_f32_16x16x32_bf16 v[130:133], v[158:161], v[190:193], v[130:133]
	v_mfma_f32_16x16x32_bf16 v[118:121], v[150:153], v[204:207], v[118:121]
	v_mfma_f32_16x16x32_bf16 v[114:117], v[158:161], v[204:207], v[114:117]
	v_mfma_f32_16x16x32_bf16 v[100:103], v[150:153], v[212:215], v[100:103]
	v_mfma_f32_16x16x32_bf16 v[96:99], v[158:161], v[212:215], v[96:99]
	v_mfma_f32_16x16x32_bf16 v[84:87], v[150:153], v[238:241], v[84:87]
	v_mfma_f32_16x16x32_bf16 v[80:83], v[158:161], v[238:241], v[80:83]
	v_mfma_f32_16x16x32_bf16 v[134:137], v[154:157], v[200:203], v[134:137]
	v_mfma_f32_16x16x32_bf16 v[130:133], v[170:173], v[200:203], v[130:133]
	v_mfma_f32_16x16x32_bf16 v[118:121], v[154:157], v[208:211], v[118:121]
	v_mfma_f32_16x16x32_bf16 v[114:117], v[170:173], v[208:211], v[114:117]
	v_mfma_f32_16x16x32_bf16 v[100:103], v[154:157], v[234:237], v[100:103]
	v_mfma_f32_16x16x32_bf16 v[96:99], v[170:173], v[234:237], v[96:99]
	v_mfma_f32_16x16x32_bf16 v[84:87], v[154:157], v[242:245], v[84:87]
	v_mfma_f32_16x16x32_bf16 v[80:83], v[170:173], v[242:245], v[80:83]
	v_mfma_f32_16x16x32_bf16 v[126:129], v[174:177], v[190:193], v[126:129]
	v_mfma_f32_16x16x32_bf16 v[122:125], v[182:185], v[190:193], v[122:125]
	v_mfma_f32_16x16x32_bf16 v[108:111], v[174:177], v[204:207], v[108:111]
	v_mfma_f32_16x16x32_bf16 v[104:107], v[182:185], v[204:207], v[104:107]
	v_mfma_f32_16x16x32_bf16 v[92:95], v[174:177], v[212:215], v[92:95]
	v_mfma_f32_16x16x32_bf16 v[88:91], v[182:185], v[212:215], v[88:91]
	v_mfma_f32_16x16x32_bf16 v[76:79], v[174:177], v[238:241], v[76:79]
	v_mfma_f32_16x16x32_bf16 v[72:75], v[182:185], v[238:241], v[72:75]
	v_mfma_f32_16x16x32_bf16 v[126:129], v[178:181], v[200:203], v[126:129]
	v_mfma_f32_16x16x32_bf16 v[122:125], v[186:189], v[200:203], v[122:125]
	v_mfma_f32_16x16x32_bf16 v[108:111], v[178:181], v[208:211], v[108:111]
	v_mfma_f32_16x16x32_bf16 v[104:107], v[186:189], v[208:211], v[104:107]
	v_mfma_f32_16x16x32_bf16 v[92:95], v[178:181], v[234:237], v[92:95]
	v_mfma_f32_16x16x32_bf16 v[88:91], v[186:189], v[234:237], v[88:91]
	v_mfma_f32_16x16x32_bf16 v[76:79], v[178:181], v[242:245], v[76:79]
	v_mfma_f32_16x16x32_bf16 v[72:75], v[186:189], v[242:245], v[72:75]
	s_setprio 0
	s_barrier
	s_add_i32 s8, s13, s81
	s_add_u32 s100, s94, 0x80
	s_addc_u32 s101, s95, 0
	s_mov_b32 m0, s8
	ds_read_b128 v[190:193], v169 offset:49152
	ds_read_b128 v[200:203], v169 offset:50176
	ds_read_b128 v[204:207], v169 offset:51200
	ds_read_b128 v[208:211], v169 offset:52224
	ds_read_b128 v[212:215], v169 offset:53248
	ds_read_b128 v[234:237], v169 offset:54272
	ds_read_b128 v[238:241], v169 offset:55296
	ds_read_b128 v[242:245], v169 offset:56320
	global_load_lds_dwordx4 v112, s[100:101]
	s_add_i32 m0, s8, 0x2000
	s_add_u32 s8, s94, 0x40080
	v_lshl_add_u64 v[162:163], v[228:229], 0, s[24:25]
	s_addc_u32 s9, s95, 0
	s_add_i32 s13, s31, s81
	global_load_lds_dwordx4 v[162:163], off
	s_nop 0
	s_mov_b32 m0, s13
	s_nop 0
	global_load_lds_dwordx4 v112, s[8:9]
	s_nop 0
	s_add_i32 m0, s13, 0x2000
	s_nop 0
	global_load_lds_dwordx4 v142, s[8:9]
	s_add_u32 s100, vcc_lo, 0x80
	s_addc_u32 s101, vcc_hi, 0
	s_mov_b32 m0, s38
	s_nop 0
	global_load_lds_dwordx4 v138, s[100:101]
	s_add_u32 s100, vcc_lo, 0x80
	s_addc_u32 s101, vcc_hi, 0
	s_mov_b32 m0, s39
	s_nop 0
	global_load_lds_dwordx4 v140, s[100:101]
	s_waitcnt vmcnt(8)
	s_waitcnt lgkmcnt(0)
	s_barrier
	s_setprio 1
	s_waitcnt lgkmcnt(0)
	v_mfma_f32_16x16x32_bf16 v[68:71], v[150:153], v[190:193], v[68:71]
	v_mfma_f32_16x16x32_bf16 v[64:67], v[158:161], v[190:193], v[64:67]
	v_mfma_f32_16x16x32_bf16 v[52:55], v[150:153], v[204:207], v[52:55]
	v_mfma_f32_16x16x32_bf16 v[48:51], v[158:161], v[204:207], v[48:51]
	v_mfma_f32_16x16x32_bf16 v[36:39], v[150:153], v[212:215], v[36:39]
	v_mfma_f32_16x16x32_bf16 v[32:35], v[158:161], v[212:215], v[32:35]
	v_mfma_f32_16x16x32_bf16 v[20:23], v[150:153], v[238:241], v[20:23]
	v_mfma_f32_16x16x32_bf16 v[16:19], v[158:161], v[238:241], v[16:19]
	v_mfma_f32_16x16x32_bf16 v[68:71], v[154:157], v[200:203], v[68:71]
	v_mfma_f32_16x16x32_bf16 v[64:67], v[170:173], v[200:203], v[64:67]
	v_mfma_f32_16x16x32_bf16 v[52:55], v[154:157], v[208:211], v[52:55]
	v_mfma_f32_16x16x32_bf16 v[48:51], v[170:173], v[208:211], v[48:51]
	v_mfma_f32_16x16x32_bf16 v[36:39], v[154:157], v[234:237], v[36:39]
	v_mfma_f32_16x16x32_bf16 v[32:35], v[170:173], v[234:237], v[32:35]
	v_mfma_f32_16x16x32_bf16 v[20:23], v[154:157], v[242:245], v[20:23]
	v_mfma_f32_16x16x32_bf16 v[16:19], v[170:173], v[242:245], v[16:19]
	v_mfma_f32_16x16x32_bf16 v[60:63], v[174:177], v[190:193], v[60:63]
	v_mfma_f32_16x16x32_bf16 v[56:59], v[182:185], v[190:193], v[56:59]
	v_mfma_f32_16x16x32_bf16 v[44:47], v[174:177], v[204:207], v[44:47]
	v_mfma_f32_16x16x32_bf16 v[40:43], v[182:185], v[204:207], v[40:43]
	v_mfma_f32_16x16x32_bf16 v[28:31], v[174:177], v[212:215], v[28:31]
	v_mfma_f32_16x16x32_bf16 v[24:27], v[182:185], v[212:215], v[24:27]
	v_mfma_f32_16x16x32_bf16 v[12:15], v[174:177], v[238:241], v[12:15]
	v_mfma_f32_16x16x32_bf16 v[8:11], v[182:185], v[238:241], v[8:11]
	v_mfma_f32_16x16x32_bf16 v[60:63], v[178:181], v[200:203], v[60:63]
	v_mfma_f32_16x16x32_bf16 v[56:59], v[186:189], v[200:203], v[56:59]
	v_mfma_f32_16x16x32_bf16 v[44:47], v[178:181], v[208:211], v[44:47]
	v_mfma_f32_16x16x32_bf16 v[40:43], v[186:189], v[208:211], v[40:43]
	v_mfma_f32_16x16x32_bf16 v[28:31], v[178:181], v[234:237], v[28:31]
	v_mfma_f32_16x16x32_bf16 v[24:27], v[186:189], v[234:237], v[24:27]
	v_mfma_f32_16x16x32_bf16 v[12:15], v[178:181], v[242:245], v[12:15]
	v_mfma_f32_16x16x32_bf16 v[8:11], v[186:189], v[242:245], v[8:11]
	s_setprio 0
	s_barrier
	s_add_i32 s85, s85, 2
	s_add_u32 s40, s40, 0x100
	s_addc_u32 s41, s41, 0
	s_add_u32 s46, s46, 0x100
	s_addc_u32 s57, s57, 0
	s_cmp_gt_u32 s85, 13
	s_cbranch_scc0 .LBB0_268
	s_and_b64 vcc, exec, s[82:83]
	s_cbranch_vccz .LBB0_271
	s_barrier
;     __device__ __forceinline__ void operator()(const f32x4 (&acc)[2][2][4][2], const Unit& u, int wr, int wc, int fr_, int fq_, int slot) const {
;         int fr = fr_, fq = fq_; asm volatile("" : "+v"(fr), "+v"(fq));
;         const int pn = u.pn;
;         const int col0 = pn * BM + wc * 32 + 8 * fq;
;         float rs[2][4];
; #pragma unroll
;         for (int ai = 0; ai < 2; ++ai)
; #pragma unroll
;             for (int m = 0; m < 4; ++m) rs[ai][m] = rst[slot * 256 + ai * HALF + wr * 64 + m * 16 + fr];
; #pragma unroll
;         for (int ai = 0; ai < 2; ++ai)
; #pragma unroll
;             for (int m = 0; m < 4; ++m) {
;                 bf16_t* rowp = P + (size_t)(u.pm * BM + ai * HALF + wr * 64 + m * 16 + fr) * EVEN_IN + col0;
; #pragma unroll
;                 for (int bj = 0; bj < 2; ++bj) {
;                     f32x4 v0 = acc[ai][bj][m][0] * rs[ai][m], v1 = acc[ai][bj][m][1] * rs[ai][m];
;                     *(u32x4*)(rowp + bj * HALF) = pack8(v0, v1);
;                 }
;                 asm volatile("" ::: "memory");
;             }
;     }
;     __device__ __forceinline__ void post(int slot, int tid, const f32x4 (&r)[2]) const {
;         const f32x4 t = r[0] + r[1]; float s = (t[0] + t[1]) + (t[2] + t[3]);
;         s += __shfl_xor(s, 1);
;         if ((tid & 1) == 0) rst[slot * 256 + (tid >> 1)] = __builtin_amdgcn_rsqf(s * (1.0f / 1024.0f) + EPS);
;     }
;     __device__ __forceinline__ void operator()(const f32x4 (&acc)[2][2][4][2], const Unit& u, int wr, int wc, int fr_, int fq_, int slot) const {
;         int fr = fr_, fq = fq_; asm volatile("" : "+v"(fr), "+v"(fq));
;         const int pn = u.pn, col0 = pn * BM + wc * 32 + 8 * fq;
;         float rs[2][4];
; #pragma unroll
;         for (int ai = 0; ai < 2; ++ai)
; #pragma unroll
;             for (int m = 0; m < 4; ++m) rs[ai][m] = rst[slot * 256 + ai * HALF + wr * 64 + m * 16 + fr];
; #pragma unroll
;         for (int ai = 0; ai < 2; ++ai)
; #pragma unroll
;             for (int m = 0; m < 4; ++m) {
;                 const int row = u.pm * BM + ai * HALF + wr * 64 + m * 16 + fr;
;                 const float r = rs[ai][m];
;                 bf16_t* rowp = P + (size_t)row * ODD_IN + col0;
;                 float sq = 0.f;
; #pragma unroll
;                 for (int bj = 0; bj < 2; ++bj) {
;                     f32x4 v0 = acc[ai][bj][m][0] * r, v1 = acc[ai][bj][m][1] * r;
.LBB0_271:
	v_cndmask_b32_e64 v150, 0, 1, s[42:43]
	v_cmp_ne_u32_e64 s[40:41], 1, v150
	s_andn2_b64 vcc, exec, s[42:43]
	s_movk_i32 s33, 0x1800
	s_cbranch_vccnz .LBB0_273
	s_lshl_b64 s[8:9], s[86:87], 14
.LBB0_273:
	s_lshl_b32 s8, s22, 10
	s_and_b32 s8, s8, 0x400
	v_mov_b32_e32 v172, v165
	v_mov_b32_e32 v170, v166
	v_lshrrev_b32_e32 v200, 2, v165
	v_lshl_add_u32 v200, v166, 2, v200
	v_and_b32_e32 v201, 3, v165
	v_lshrrev_b32_e32 v202, 6, v233
	v_lshlrev_b32_e32 v202, 11, v202
	v_add_u32_e32 v202, 0x20000, v202
	v_mul_u32_u24_e32 v203, 0x50, v165
	v_lshl_add_u32 v203, v166, 4, v203
	v_add_u32_e32 v203, v203, v202
	v_mul_u32_u24_e32 v204, 0x50, v200
	v_lshl_add_u32 v204, v201, 4, v204
	v_add_u32_e32 v204, v204, v202
	s_add_i32 s8, s30, s8
	v_mov_b32_e32 v171, 0
	v_lshl_add_u32 v150, v172, 2, s8
	ds_read2_b32 v[156:157], v150 offset1:16
	ds_read2_b32 v[154:155], v150 offset0:32 offset1:48
	ds_read2_b32 v[152:153], v150 offset0:128 offset1:144
	ds_read2_b32 v[150:151], v150 offset0:160 offset1:176
	s_and_b32 s8, s92, -4
	s_cmp_eq_u32 s8, 4
	s_cselect_b64 s[94:95], -1, 0
	s_cmp_lg_u32 s8, 4
	s_waitcnt lgkmcnt(0)
	v_pk_mul_f32 v[160:161], v[136:137], v[156:157] op_sel_hi:[1,0]
	v_pk_mul_f32 v[162:163], v[134:135], v[156:157] op_sel_hi:[1,0]
	v_pk_mul_f32 v[136:137], v[132:133], v[156:157] op_sel_hi:[1,0]
	v_pk_mul_f32 v[158:159], v[130:131], v[156:157] op_sel_hi:[1,0]
	s_cbranch_scc1 .LBB0_275
	v_and_b32_e32 v177, 0x7fffffff, v161
	v_and_b32_e32 v176, 0x7fffffff, v160
	v_pk_fma_f32 v[176:177], v[176:177], s[14:15], 1.0 op_sel_hi:[1,0,0]
	s_mov_b32 s8, 0xbf3a00e3
	v_rcp_f32_e32 v176, v176
	v_rcp_f32_e32 v177, v177
	v_mov_b64_e32 v[132:133], s[8:9]
	v_and_b32_e32 v131, 0x7fffffff, v163
	v_and_b32_e32 v130, 0x7fffffff, v162
	v_pk_fma_f32 v[178:179], v[176:177], s[34:35], v[132:133] op_sel_hi:[1,0,0]
	v_pk_fma_f32 v[130:131], v[130:131], s[14:15], 1.0 op_sel_hi:[1,0,0]
	v_pk_fma_f32 v[178:179], v[176:177], v[178:179], s[56:57] op_sel_hi:[1,1,0]
	v_rcp_f32_e32 v130, v130
	v_pk_fma_f32 v[178:179], v[176:177], v[178:179], s[10:11] op_sel_hi:[1,1,0]
	v_rcp_f32_e32 v131, v131
	v_pk_fma_f32 v[178:179], v[176:177], v[178:179], s[18:19] op_sel_hi:[1,1,0]
	v_and_b32_e32 v185, 0x7fffffff, v137
	v_pk_mul_f32 v[176:177], v[176:177], v[178:179]
	v_and_b32_e32 v179, 0x7fffffff, v159
	v_and_b32_e32 v178, 0x7fffffff, v158
	v_pk_fma_f32 v[178:179], v[178:179], s[14:15], 1.0 op_sel_hi:[1,0,0]
	v_and_b32_e32 v184, 0x7fffffff, v136
	v_rcp_f32_e32 v178, v178
	v_rcp_f32_e32 v179, v179
	v_pk_fma_f32 v[184:185], v[184:185], s[14:15], 1.0 op_sel_hi:[1,0,0]
	v_pk_mul_f32 v[182:183], v[158:159], v[158:159]
	v_rcp_f32_e32 v184, v184
	v_pk_fma_f32 v[180:181], v[178:179], s[34:35], v[132:133] op_sel_hi:[1,0,0]
	v_rcp_f32_e32 v185, v185
	v_pk_fma_f32 v[134:135], v[130:131], s[34:35], v[132:133] op_sel_hi:[1,0,0]
	v_pk_mul_f32 v[174:175], v[162:163], v[162:163]
	v_pk_fma_f32 v[180:181], v[178:179], v[180:181], s[56:57] op_sel_hi:[1,1,0]
	v_pk_mul_f32 v[182:183], v[182:183], s[12:13] op_sel_hi:[1,0]
	v_pk_fma_f32 v[134:135], v[130:131], v[134:135], s[56:57] op_sel_hi:[1,1,0]
	v_pk_mul_f32 v[174:175], v[174:175], s[12:13] op_sel_hi:[1,0]
	v_pk_fma_f32 v[180:181], v[178:179], v[180:181], s[10:11] op_sel_hi:[1,1,0]
	v_exp_f32_e32 v182, v182
	v_exp_f32_e32 v183, v183
	v_pk_fma_f32 v[134:135], v[130:131], v[134:135], s[10:11] op_sel_hi:[1,1,0]
	v_exp_f32_e32 v174, v174
	v_exp_f32_e32 v175, v175
	v_pk_fma_f32 v[180:181], v[178:179], v[180:181], s[18:19] op_sel_hi:[1,1,0]
	v_pk_fma_f32 v[134:135], v[130:131], v[134:135], s[18:19] op_sel_hi:[1,1,0]
	v_pk_mul_f32 v[178:179], v[178:179], v[180:181]
	v_pk_mul_f32 v[180:181], v[136:137], v[136:137]
	v_pk_fma_f32 v[132:133], v[184:185], s[34:35], v[132:133] op_sel_hi:[1,0,0]
	v_pk_mul_f32 v[130:131], v[130:131], v[134:135]
	v_pk_mul_f32 v[134:135], v[160:161], v[160:161]
	v_pk_fma_f32 v[132:133], v[184:185], v[132:133], s[56:57] op_sel_hi:[1,1,0]
	v_pk_mul_f32 v[180:181], v[180:181], s[12:13] op_sel_hi:[1,0]
	v_pk_mul_f32 v[134:135], v[134:135], s[12:13] op_sel_hi:[1,0]
	v_pk_mul_f32 v[178:179], v[182:183], v[178:179]
	v_exp_f32_e32 v180, v180
	v_exp_f32_e32 v181, v181
	v_pk_fma_f32 v[132:133], v[184:185], v[132:133], s[10:11] op_sel_hi:[1,1,0]
	v_pk_mul_f32 v[130:131], v[174:175], v[130:131]
	v_exp_f32_e32 v134, v134
	v_exp_f32_e32 v135, v135
	v_pk_mul_f32 v[182:183], v[158:159], v[178:179]
	v_pk_fma_f32 v[178:179], v[158:159], v[178:179], v[158:159] neg_lo:[1,0,0] neg_hi:[1,0,0]
	v_pk_fma_f32 v[132:133], v[184:185], v[132:133], s[18:19] op_sel_hi:[1,1,0]
	v_cmp_gt_f32_e32 vcc, 0, v158
	v_pk_mul_f32 v[174:175], v[162:163], v[130:131]
	v_pk_fma_f32 v[130:131], v[162:163], v[130:131], v[162:163] neg_lo:[1,0,0] neg_hi:[1,0,0]
	v_pk_mul_f32 v[132:133], v[184:185], v[132:133]
	v_cndmask_b32_e32 v185, v178, v182, vcc
	v_cmp_gt_f32_e32 vcc, 0, v162
	v_pk_mul_f32 v[132:133], v[180:181], v[132:133]
	v_pk_mul_f32 v[134:135], v[134:135], v[176:177]
	v_cndmask_b32_e32 v184, v130, v174, vcc
	v_cmp_gt_f32_e32 vcc, 0, v159
	v_pk_mul_f32 v[180:181], v[136:137], v[132:133]
	v_pk_fma_f32 v[132:133], v[136:137], v[132:133], v[136:137] neg_lo:[1,0,0] neg_hi:[1,0,0]
	v_cndmask_b32_e32 v159, v179, v183, vcc
	v_cmp_gt_f32_e32 vcc, 0, v163
	v_pk_mul_f32 v[176:177], v[160:161], v[134:135]
	v_pk_fma_f32 v[134:135], v[160:161], v[134:135], v[160:161] neg_lo:[1,0,0] neg_hi:[1,0,0]
	v_cndmask_b32_e32 v158, v131, v175, vcc
	v_cmp_gt_f32_e32 vcc, 0, v136
	v_mov_b32_e32 v162, v184
	v_mov_b32_e32 v163, v158
	v_cndmask_b32_e32 v131, v132, v180, vcc
	v_cmp_gt_f32_e32 vcc, 0, v160
	s_nop 1
	v_cndmask_b32_e32 v130, v134, v176, vcc
	v_cmp_gt_f32_e32 vcc, 0, v137
	v_mov_b32_e32 v160, v130
	s_nop 0
	v_cndmask_b32_e32 v137, v133, v181, vcc
	v_cmp_gt_f32_e32 vcc, 0, v161
	v_pk_mul_f32 v[132:133], v[158:159], v[158:159]
	v_mov_b32_e32 v158, v185
	v_cndmask_b32_e32 v136, v135, v177, vcc
	v_pk_mul_f32 v[134:135], v[136:137], v[136:137]
	v_pk_fma_f32 v[132:133], v[184:185], v[184:185], v[132:133]
	v_pk_fma_f32 v[134:135], v[130:131], v[130:131], v[134:135]
	v_mov_b32_e32 v161, v136
	v_pk_add_f32 v[132:133], v[132:133], v[134:135]
	v_mov_b32_e32 v136, v131
	v_add_f32_e32 v171, v132, v133

; template <class Epi>
; __device__ __forceinline__ void gemm_phase(LAS unsigned char* lds, const Gemm g, const StaticOrder& S, const Epi& E, const int tid) {
;     ...
;     for (;;) {
;         const bool has_next = S.next(ui + 1, nxt);
;         const char* nA = has_next ? (const char*)g.A + (size_t)nxt.pm * tstepA : cA; const char* nB = has_next ? (const char*)g.Bt + (size_t)nxt.pn * tstepB : cB;
;     ...
; #pragma unroll
;         for (int a = 0; a < 2; ++a)
; #pragma unroll
;             for (int b = 0; b < 2; ++b)
; #pragma unroll
;                 for (int m = 0; m < 4; ++m)
; #pragma unroll
;                     for (int n = 0; n < 2; ++n) acc[a][b][m][n] = (f32x4){0.f, 0.f, 0.f, 0.f};
;         cur = nxt; cA = nA; cB = nB; ++ui;
.LBB0_355:
	s_ashr_i32 s85, s84, 31
	s_lshl_b64 s[86:87], s[84:85], 19
	s_add_u32 s86, s6, s86
	s_addc_u32 s87, s7, s87
	s_and_b64 s[88:89], s[40:41], exec
	s_cselect_b32 s98, s87, s43
	s_cselect_b32 s99, s86, s42
	s_ashr_i32 s83, s82, 31
	s_lshl_b64 s[88:89], s[82:83], 19
	s_add_u32 s88, s11, s88
	s_addc_u32 s89, s16, s89
	s_and_b64 s[94:95], s[40:41], exec
	s_cselect_b32 s83, s89, s93
	s_cselect_b32 vcc_lo, s88, s92
	s_add_u32 s42, s42, 0x40080
	s_addc_u32 s43, s43, 0
	s_add_u32 vcc_hi, s92, 0x100
	v_mov_b32_e32 v8, 0
	s_addc_u32 s96, s93, 0
	s_mov_b32 s97, -2
	v_mov_b32_e32 v9, v8
	v_mov_b32_e32 v10, v8
	v_mov_b32_e32 v11, v8
	v_mov_b32_e32 v12, v8
	v_mov_b32_e32 v13, v8
	v_mov_b32_e32 v14, v8
	v_mov_b32_e32 v15, v8
	v_mov_b32_e32 v20, v8
	v_mov_b32_e32 v21, v8
	v_mov_b32_e32 v22, v8
	v_mov_b32_e32 v23, v8
	v_mov_b32_e32 v28, v8
	v_mov_b32_e32 v29, v8
	v_mov_b32_e32 v30, v8
	v_mov_b32_e32 v31, v8
	v_mov_b32_e32 v36, v8
	v_mov_b32_e32 v37, v8
	v_mov_b32_e32 v38, v8
	v_mov_b32_e32 v39, v8
	v_mov_b32_e32 v44, v8
	v_mov_b32_e32 v45, v8
	v_mov_b32_e32 v46, v8
	v_mov_b32_e32 v47, v8
	v_mov_b32_e32 v52, v8
	v_mov_b32_e32 v53, v8
	v_mov_b32_e32 v54, v8
	v_mov_b32_e32 v55, v8
	v_mov_b32_e32 v60, v8
	v_mov_b32_e32 v61, v8
	v_mov_b32_e32 v62, v8
	v_mov_b32_e32 v63, v8
	v_mov_b32_e32 v16, v8
	v_mov_b32_e32 v17, v8
	v_mov_b32_e32 v18, v8
	v_mov_b32_e32 v19, v8
	v_mov_b32_e32 v24, v8
	v_mov_b32_e32 v25, v8
	v_mov_b32_e32 v26, v8
	v_mov_b32_e32 v27, v8
	v_mov_b32_e32 v32, v8
	v_mov_b32_e32 v33, v8
	v_mov_b32_e32 v34, v8
	v_mov_b32_e32 v35, v8
	v_mov_b32_e32 v40, v8
	v_mov_b32_e32 v41, v8
	v_mov_b32_e32 v42, v8
	v_mov_b32_e32 v43, v8
	v_mov_b32_e32 v48, v8
	v_mov_b32_e32 v49, v8
	v_mov_b32_e32 v50, v8
	v_mov_b32_e32 v51, v8
	v_mov_b32_e32 v56, v8
	v_mov_b32_e32 v57, v8
	v_mov_b32_e32 v58, v8
	v_mov_b32_e32 v59, v8
	v_mov_b32_e32 v64, v8
	v_mov_b32_e32 v65, v8
	v_mov_b32_e32 v66, v8
	v_mov_b32_e32 v67, v8
	v_mov_b32_e32 v68, v8
	v_mov_b32_e32 v69, v8
	v_mov_b32_e32 v70, v8
	v_mov_b32_e32 v71, v8
	v_mov_b32_e32 v72, v8
	v_mov_b32_e32 v73, v8
	v_mov_b32_e32 v74, v8
	v_mov_b32_e32 v75, v8
	v_mov_b32_e32 v76, v8
	v_mov_b32_e32 v77, v8
	v_mov_b32_e32 v78, v8
	v_mov_b32_e32 v79, v8
	v_mov_b32_e32 v84, v8
	v_mov_b32_e32 v85, v8
	v_mov_b32_e32 v86, v8
	v_mov_b32_e32 v87, v8
	v_mov_b32_e32 v92, v8
	v_mov_b32_e32 v93, v8
	v_mov_b32_e32 v94, v8
	v_mov_b32_e32 v95, v8
	v_mov_b32_e32 v100, v8
	v_mov_b32_e32 v101, v8
	v_mov_b32_e32 v102, v8
	v_mov_b32_e32 v103, v8
	v_mov_b32_e32 v108, v8
	v_mov_b32_e32 v109, v8
	v_mov_b32_e32 v110, v8
	v_mov_b32_e32 v111, v8
	v_mov_b32_e32 v118, v8
	v_mov_b32_e32 v119, v8
	v_mov_b32_e32 v120, v8
	v_mov_b32_e32 v121, v8
	v_mov_b32_e32 v126, v8
	v_mov_b32_e32 v127, v8
	v_mov_b32_e32 v128, v8
	v_mov_b32_e32 v129, v8
	v_mov_b32_e32 v80, v8
	v_mov_b32_e32 v81, v8
	v_mov_b32_e32 v82, v8
	v_mov_b32_e32 v83, v8
	v_mov_b32_e32 v88, v8
	v_mov_b32_e32 v89, v8
	v_mov_b32_e32 v90, v8
	v_mov_b32_e32 v91, v8
	v_mov_b32_e32 v96, v8
	v_mov_b32_e32 v97, v8
	v_mov_b32_e32 v98, v8
	v_mov_b32_e32 v99, v8
	v_mov_b32_e32 v104, v8
	v_mov_b32_e32 v105, v8
	v_mov_b32_e32 v106, v8
	v_mov_b32_e32 v107, v8
	v_mov_b32_e32 v114, v8
	v_mov_b32_e32 v115, v8
	v_mov_b32_e32 v116, v8
	v_mov_b32_e32 v117, v8
	v_mov_b32_e32 v122, v8
	v_mov_b32_e32 v123, v8
	v_mov_b32_e32 v124, v8
	v_mov_b32_e32 v125, v8
	v_mov_b32_e32 v130, v8
	v_mov_b32_e32 v131, v8
	v_mov_b32_e32 v132, v8
	v_mov_b32_e32 v133, v8
	v_mov_b32_e32 v134, v8
	v_mov_b32_e32 v135, v8
	v_mov_b32_e32 v136, v8
	v_mov_b32_e32 v137, v8
	s_and_b64 s[8:9], exec, s[40:41]
	s_cbranch_scc0 .Lbias_skip_e
	s_lshl_b64 s[8:9], s[84:85], 14
	v_lshl_add_u64 v[4:5], v[144:145], 0, s[8:9]
	global_load_dwordx4 v[0:3], v[4:5], off offset:16
	s_nop 0
	global_load_dwordx4 v[4:7], v[4:5], off
.Lbias_skip_e:
.LBB0_356:
	s_add_u32 s8, s42, 0xfffc0080
	s_addc_u32 s9, s43, -1
	s_add_i32 s13, 0, 0x10000
	v_add_u32_e32 v168, s13, v161
	v_add_u32_e32 v184, s15, v161
	ds_read_b128 v[150:153], v168
	ds_read_b128 v[154:157], v168 offset:1024
	ds_read_b128 v[164:167], v168 offset:2048
	ds_read_b128 v[168:171], v168 offset:3072
	ds_read_b128 v[172:175], v184
	ds_read_b128 v[176:179], v184 offset:1024
	ds_read_b128 v[180:183], v184 offset:2048
	ds_read_b128 v[184:187], v184 offset:3072
	s_cmp_eq_u32 s97, 12
	s_cselect_b32 s95, s98, s9
	s_cselect_b32 s94, s99, s8
	s_cselect_b32 s93, s83, s96
	s_cselect_b32 s92, vcc_lo, vcc_hi
	s_nop 0
	s_add_i32 m0, s19, 0xc000
	ds_read_b128 v[188:191], v163
	ds_read_b128 v[200:203], v163 offset:1024
	ds_read_b128 v[204:207], v163 offset:2048
	ds_read_b128 v[208:211], v163 offset:3072
	ds_read_b128 v[212:215], v163 offset:4096
	ds_read_b128 v[234:237], v163 offset:5120
	ds_read_b128 v[238:241], v163 offset:6144
	ds_read_b128 v[242:245], v163 offset:7168
	global_load_lds_dwordx4 v146, s[42:43]
	s_nop 0
	s_add_i32 m0, s19, 0xe000
	s_nop 0
	global_load_lds_dwordx4 v148, s[42:43]
	s_waitcnt vmcnt(8)
	s_waitcnt lgkmcnt(0)
	s_barrier
; #define PG8_STAGE(bufoff, gbase, voff) do { _Pragma("unroll") for (int _i = 0; _i < 2; ++_i) \
;         __builtin_amdgcn_global_load_lds((const unsigned*)((const char*)(gbase) + (voff)[_i]), (LAS unsigned*)(lds + (bufoff) + ldsw + _i * 8192), 16, 0, 0); } while (0)
; #define PG8_LDA(dst, b, h) do { _Pragma("unroll") for (int m = 0; m < 4; ++m) _Pragma("unroll") for (int k = 0; k < 2; ++k) dst[m][k] = *(const LAS bf16x8*)(lds + PG8_SA(b, h) + aoff + m * 2048 + k * 1024); } while (0)
; #define PG8_LDB(dst, b, h) do { _Pragma("unroll") for (int n = 0; n < 2; ++n) _Pragma("unroll") for (int k = 0; k < 2; ++k) dst[n][k] = *(const LAS bf16x8*)(lds + PG8_SB(b, h) + boff + n * 2048 + k * 1024); } while (0)
; #define PG8_MMA(ai, bj, At, Bt) do { __builtin_amdgcn_s_setprio(1); _Pragma("unroll") for (int m = 0; m < 4; ++m) _Pragma("unroll") for (int n = 0; n < 2; ++n) _Pragma("unroll") for (int k = 0; k < 2; ++k) \
;         acc[ai][bj][m][n] = __builtin_amdgcn_mfma_f32_16x16x32_bf16(Bt[n][k], At[m][k], acc[ai][bj][m][n], 0, 0, 0); __builtin_amdgcn_s_setprio(0); } while (0)
; #define PG8_WAIT_V(n) asm volatile("s_waitcnt vmcnt(" #n ")" ::: "memory")
; #define PG8_WAIT_L(n) asm volatile("s_waitcnt lgkmcnt(" #n ")" ::: "memory")
; #define PG8_BAR __builtin_amdgcn_s_barrier()
; #define PG8_SCHED __builtin_amdgcn_sched_barrier(0)
; template <class Epi>
; __device__ __forceinline__ void gemm_phase(LAS unsigned char* lds, const Gemm g, const StaticOrder& S, const Epi& E, const int tid) {
;     ...
;             PG8_LDB(B0, 0, 0); PG8_LDB(B1, 0, 1); PG8_SCHED; PG8_LDA(At, 0, 0); PG8_STAGE(PG8_SA(1, 1), a1 + hstepA, voffA);
;             PG8_WAIT_V(8); PG8_WAIT_L(0); PG8_BAR; PG8_MMA(0, 0, At, B0); PG8_MMA(0, 1, At, B1); PG8_BAR; PG8_SCHED;
;             PG8_LDA(At, 0, 1); PG8_STAGE(PG8_SB(0, 0), b2, voffB); PG8_STAGE(PG8_SB(0, 1), b2 + hstepB, voffB); PG8_STAGE(PG8_SA(0, 0), a2, voffA);
;             PG8_WAIT_V(8); PG8_WAIT_L(0); PG8_BAR; PG8_MMA(1, 0, At, B0); PG8_MMA(1, 1, At, B1); PG8_BAR; PG8_SCHED;
	s_setprio 1
	s_waitcnt lgkmcnt(0)
	v_mfma_f32_16x16x32_bf16 v[134:137], v[150:153], v[188:191], v[134:137]
	v_mfma_f32_16x16x32_bf16 v[130:133], v[164:167], v[188:191], v[130:133]
	v_mfma_f32_16x16x32_bf16 v[122:125], v[150:153], v[204:207], v[122:125]
	v_mfma_f32_16x16x32_bf16 v[114:117], v[164:167], v[204:207], v[114:117]
	v_mfma_f32_16x16x32_bf16 v[104:107], v[150:153], v[212:215], v[104:107]
	v_mfma_f32_16x16x32_bf16 v[96:99], v[164:167], v[212:215], v[96:99]
	v_mfma_f32_16x16x32_bf16 v[88:91], v[150:153], v[238:241], v[88:91]
	v_mfma_f32_16x16x32_bf16 v[80:83], v[164:167], v[238:241], v[80:83]
	v_mfma_f32_16x16x32_bf16 v[134:137], v[154:157], v[200:203], v[134:137]
	v_mfma_f32_16x16x32_bf16 v[130:133], v[168:171], v[200:203], v[130:133]
	v_mfma_f32_16x16x32_bf16 v[122:125], v[154:157], v[208:211], v[122:125]
	v_mfma_f32_16x16x32_bf16 v[114:117], v[168:171], v[208:211], v[114:117]
	v_mfma_f32_16x16x32_bf16 v[104:107], v[154:157], v[234:237], v[104:107]
	v_mfma_f32_16x16x32_bf16 v[96:99], v[168:171], v[234:237], v[96:99]
	v_mfma_f32_16x16x32_bf16 v[88:91], v[154:157], v[242:245], v[88:91]
	v_mfma_f32_16x16x32_bf16 v[80:83], v[168:171], v[242:245], v[80:83]
	v_mfma_f32_16x16x32_bf16 v[126:129], v[172:175], v[188:191], v[126:129]
	v_mfma_f32_16x16x32_bf16 v[118:121], v[180:183], v[188:191], v[118:121]
	v_mfma_f32_16x16x32_bf16 v[108:111], v[172:175], v[204:207], v[108:111]
	v_mfma_f32_16x16x32_bf16 v[100:103], v[180:183], v[204:207], v[100:103]
	v_mfma_f32_16x16x32_bf16 v[92:95], v[172:175], v[212:215], v[92:95]
	v_mfma_f32_16x16x32_bf16 v[84:87], v[180:183], v[212:215], v[84:87]
	v_mfma_f32_16x16x32_bf16 v[76:79], v[172:175], v[238:241], v[76:79]
	v_mfma_f32_16x16x32_bf16 v[72:75], v[180:183], v[238:241], v[72:75]
	v_mfma_f32_16x16x32_bf16 v[126:129], v[176:179], v[200:203], v[126:129]
	v_mfma_f32_16x16x32_bf16 v[118:121], v[184:187], v[200:203], v[118:121]
	v_mfma_f32_16x16x32_bf16 v[108:111], v[176:179], v[208:211], v[108:111]
	v_mfma_f32_16x16x32_bf16 v[100:103], v[184:187], v[208:211], v[100:103]
	v_mfma_f32_16x16x32_bf16 v[92:95], v[176:179], v[234:237], v[92:95]
	v_mfma_f32_16x16x32_bf16 v[84:87], v[184:187], v[234:237], v[84:87]
	v_mfma_f32_16x16x32_bf16 v[76:79], v[176:179], v[242:245], v[76:79]
	v_mfma_f32_16x16x32_bf16 v[72:75], v[184:187], v[242:245], v[72:75]
	s_setprio 0
	s_barrier
	s_add_i32 s8, s13, s17
	s_nop 0
	s_mov_b32 m0, s8
	ds_read_b128 v[188:191], v163 offset:16384
	ds_read_b128 v[200:203], v163 offset:17408
	ds_read_b128 v[204:207], v163 offset:18432
	ds_read_b128 v[208:211], v163 offset:19456
	ds_read_b128 v[212:215], v163 offset:20480
	ds_read_b128 v[234:237], v163 offset:21504
	ds_read_b128 v[238:241], v163 offset:22528
	ds_read_b128 v[242:245], v163 offset:23552
	global_load_lds_dwordx4 v112, s[92:93]
	s_add_i32 m0, s8, 0x2000
	s_add_u32 s8, s92, 0x40000
	v_lshl_add_u64 v[246:247], s[92:93], 0, v[142:143]
	s_addc_u32 s9, s93, 0
	s_add_i32 s13, s15, s17
	global_load_lds_dwordx4 v142, s[92:93]
	s_nop 0
	s_mov_b32 m0, s13
	s_nop 0
	global_load_lds_dwordx4 v112, s[8:9]
	s_nop 0
	s_add_i32 m0, s13, 0x2000
	s_nop 0
	global_load_lds_dwordx4 v142, s[8:9]
	s_nop 0
	s_mov_b32 m0, s19
	s_nop 0
	global_load_lds_dwordx4 v138, s[94:95]
	s_mov_b32 m0, s23
	s_nop 0
	global_load_lds_dwordx4 v140, s[94:95]
	s_waitcnt vmcnt(8)
	s_waitcnt lgkmcnt(0)
	s_barrier
	s_setprio 1
	s_waitcnt lgkmcnt(0)
	v_mfma_f32_16x16x32_bf16 v[68:71], v[150:153], v[188:191], v[68:71]
	v_mfma_f32_16x16x32_bf16 v[64:67], v[164:167], v[188:191], v[64:67]
	v_mfma_f32_16x16x32_bf16 v[56:59], v[150:153], v[204:207], v[56:59]
	v_mfma_f32_16x16x32_bf16 v[48:51], v[164:167], v[204:207], v[48:51]
	v_mfma_f32_16x16x32_bf16 v[40:43], v[150:153], v[212:215], v[40:43]
	v_mfma_f32_16x16x32_bf16 v[32:35], v[164:167], v[212:215], v[32:35]
	v_mfma_f32_16x16x32_bf16 v[24:27], v[150:153], v[238:241], v[24:27]
	v_mfma_f32_16x16x32_bf16 v[16:19], v[164:167], v[238:241], v[16:19]
	v_mfma_f32_16x16x32_bf16 v[68:71], v[154:157], v[200:203], v[68:71]
	v_mfma_f32_16x16x32_bf16 v[64:67], v[168:171], v[200:203], v[64:67]
	v_mfma_f32_16x16x32_bf16 v[56:59], v[154:157], v[208:211], v[56:59]
	v_mfma_f32_16x16x32_bf16 v[48:51], v[168:171], v[208:211], v[48:51]
	v_mfma_f32_16x16x32_bf16 v[40:43], v[154:157], v[234:237], v[40:43]
	v_mfma_f32_16x16x32_bf16 v[32:35], v[168:171], v[234:237], v[32:35]
	v_mfma_f32_16x16x32_bf16 v[24:27], v[154:157], v[242:245], v[24:27]
	v_mfma_f32_16x16x32_bf16 v[16:19], v[168:171], v[242:245], v[16:19]
	v_mfma_f32_16x16x32_bf16 v[60:63], v[172:175], v[188:191], v[60:63]
	v_mfma_f32_16x16x32_bf16 v[52:55], v[180:183], v[188:191], v[52:55]
	v_mfma_f32_16x16x32_bf16 v[44:47], v[172:175], v[204:207], v[44:47]
	v_mfma_f32_16x16x32_bf16 v[36:39], v[180:183], v[204:207], v[36:39]
	v_mfma_f32_16x16x32_bf16 v[28:31], v[172:175], v[212:215], v[28:31]
	v_mfma_f32_16x16x32_bf16 v[20:23], v[180:183], v[212:215], v[20:23]
	v_mfma_f32_16x16x32_bf16 v[12:15], v[172:175], v[238:241], v[12:15]
	v_mfma_f32_16x16x32_bf16 v[8:11], v[180:183], v[238:241], v[8:11]
	v_mfma_f32_16x16x32_bf16 v[60:63], v[176:179], v[200:203], v[60:63]
	v_mfma_f32_16x16x32_bf16 v[52:55], v[184:187], v[200:203], v[52:55]
	v_mfma_f32_16x16x32_bf16 v[44:47], v[176:179], v[208:211], v[44:47]
	v_mfma_f32_16x16x32_bf16 v[36:39], v[184:187], v[208:211], v[36:39]
	v_mfma_f32_16x16x32_bf16 v[28:31], v[176:179], v[234:237], v[28:31]
	v_mfma_f32_16x16x32_bf16 v[20:23], v[184:187], v[234:237], v[20:23]
	v_mfma_f32_16x16x32_bf16 v[12:15], v[176:179], v[242:245], v[12:15]
	v_mfma_f32_16x16x32_bf16 v[8:11], v[184:187], v[242:245], v[8:11]
	s_setprio 0
	s_barrier
; #define PG8_STAGE(bufoff, gbase, voff) do { _Pragma("unroll") for (int _i = 0; _i < 2; ++_i) \
;         __builtin_amdgcn_global_load_lds((const unsigned*)((const char*)(gbase) + (voff)[_i]), (LAS unsigned*)(lds + (bufoff) + ldsw + _i * 8192), 16, 0, 0); } while (0)
; #define PG8_LDA(dst, b, h) do { _Pragma("unroll") for (int m = 0; m < 4; ++m) _Pragma("unroll") for (int k = 0; k < 2; ++k) dst[m][k] = *(const LAS bf16x8*)(lds + PG8_SA(b, h) + aoff + m * 2048 + k * 1024); } while (0)
; #define PG8_LDB(dst, b, h) do { _Pragma("unroll") for (int n = 0; n < 2; ++n) _Pragma("unroll") for (int k = 0; k < 2; ++k) dst[n][k] = *(const LAS bf16x8*)(lds + PG8_SB(b, h) + boff + n * 2048 + k * 1024); } while (0)
; #define PG8_MMA(ai, bj, At, Bt) do { __builtin_amdgcn_s_setprio(1); _Pragma("unroll") for (int m = 0; m < 4; ++m) _Pragma("unroll") for (int n = 0; n < 2; ++n) _Pragma("unroll") for (int k = 0; k < 2; ++k) \
;         acc[ai][bj][m][n] = __builtin_amdgcn_mfma_f32_16x16x32_bf16(Bt[n][k], At[m][k], acc[ai][bj][m][n], 0, 0, 0); __builtin_amdgcn_s_setprio(0); } while (0)
; #define PG8_WAIT_V(n) asm volatile("s_waitcnt vmcnt(" #n ")" ::: "memory")
; #define PG8_WAIT_L(n) asm volatile("s_waitcnt lgkmcnt(" #n ")" ::: "memory")
; #define PG8_BAR __builtin_amdgcn_s_barrier()
; #define PG8_SCHED __builtin_amdgcn_sched_barrier(0)
; template <class Epi>
; __device__ __forceinline__ void gemm_phase(LAS unsigned char* lds, const Gemm g, const StaticOrder& S, const Epi& E, const int tid) {
;     ...
;             PG8_LDB(B0, 1, 0); PG8_LDB(B1, 1, 1); PG8_SCHED; PG8_LDA(At, 1, 0); PG8_STAGE(PG8_SA(0, 1), a2 + hstepA, voffA);
;             PG8_WAIT_V(8); PG8_WAIT_L(0); PG8_BAR; PG8_MMA(0, 0, At, B0); PG8_MMA(0, 1, At, B1); PG8_BAR; PG8_SCHED;
;             PG8_LDA(At, 1, 1); PG8_STAGE(PG8_SB(1, 0), b3, voffB); PG8_STAGE(PG8_SB(1, 1), b3 + hstepB, voffB); PG8_STAGE(PG8_SA(1, 0), a3, voffA);
;             PG8_WAIT_V(8); PG8_WAIT_L(0); PG8_BAR; PG8_MMA(1, 0, At, B0); PG8_MMA(1, 1, At, B1); PG8_BAR; PG8_SCHED;
	s_add_i32 s13, 0, 0x18000
	s_add_i32 s31, 0, 0x1c000
	v_add_u32_e32 v168, s13, v161
	v_add_u32_e32 v184, s31, v161
	ds_read_b128 v[150:153], v168
	ds_read_b128 v[154:157], v168 offset:1024
	ds_read_b128 v[164:167], v168 offset:2048
	ds_read_b128 v[168:171], v168 offset:3072
	ds_read_b128 v[172:175], v184
	ds_read_b128 v[176:179], v184 offset:1024
	ds_read_b128 v[180:183], v184 offset:2048
	ds_read_b128 v[184:187], v184 offset:3072
	s_add_u32 s8, s94, 0x40000
	s_addc_u32 s9, s95, 0
	s_mov_b32 m0, s28
	s_nop 0
	ds_read_b128 v[188:191], v163 offset:32768
	ds_read_b128 v[200:203], v163 offset:33792
	ds_read_b128 v[204:207], v163 offset:34816
	ds_read_b128 v[208:211], v163 offset:35840
	ds_read_b128 v[212:215], v163 offset:36864
	ds_read_b128 v[234:237], v163 offset:37888
	ds_read_b128 v[238:241], v163 offset:38912
	ds_read_b128 v[242:245], v163 offset:39936
	global_load_lds_dwordx4 v138, s[8:9]
	s_nop 0
	s_mov_b32 m0, s30
	s_nop 0
	global_load_lds_dwordx4 v140, s[8:9]
	s_waitcnt vmcnt(8)
	s_waitcnt lgkmcnt(0)
	s_barrier
	s_setprio 1
	s_waitcnt lgkmcnt(0)
	v_mfma_f32_16x16x32_bf16 v[134:137], v[150:153], v[188:191], v[134:137]
	v_mfma_f32_16x16x32_bf16 v[130:133], v[164:167], v[188:191], v[130:133]
	v_mfma_f32_16x16x32_bf16 v[122:125], v[150:153], v[204:207], v[122:125]
	v_mfma_f32_16x16x32_bf16 v[114:117], v[164:167], v[204:207], v[114:117]
	v_mfma_f32_16x16x32_bf16 v[104:107], v[150:153], v[212:215], v[104:107]
	v_mfma_f32_16x16x32_bf16 v[96:99], v[164:167], v[212:215], v[96:99]
	v_mfma_f32_16x16x32_bf16 v[88:91], v[150:153], v[238:241], v[88:91]
	v_mfma_f32_16x16x32_bf16 v[80:83], v[164:167], v[238:241], v[80:83]
	v_mfma_f32_16x16x32_bf16 v[134:137], v[154:157], v[200:203], v[134:137]
	v_mfma_f32_16x16x32_bf16 v[130:133], v[168:171], v[200:203], v[130:133]
	v_mfma_f32_16x16x32_bf16 v[122:125], v[154:157], v[208:211], v[122:125]
	v_mfma_f32_16x16x32_bf16 v[114:117], v[168:171], v[208:211], v[114:117]
	v_mfma_f32_16x16x32_bf16 v[104:107], v[154:157], v[234:237], v[104:107]
	v_mfma_f32_16x16x32_bf16 v[96:99], v[168:171], v[234:237], v[96:99]
	v_mfma_f32_16x16x32_bf16 v[88:91], v[154:157], v[242:245], v[88:91]
	v_mfma_f32_16x16x32_bf16 v[80:83], v[168:171], v[242:245], v[80:83]
	v_mfma_f32_16x16x32_bf16 v[126:129], v[172:175], v[188:191], v[126:129]
	v_mfma_f32_16x16x32_bf16 v[118:121], v[180:183], v[188:191], v[118:121]
	v_mfma_f32_16x16x32_bf16 v[108:111], v[172:175], v[204:207], v[108:111]
	v_mfma_f32_16x16x32_bf16 v[100:103], v[180:183], v[204:207], v[100:103]
	v_mfma_f32_16x16x32_bf16 v[92:95], v[172:175], v[212:215], v[92:95]
	v_mfma_f32_16x16x32_bf16 v[84:87], v[180:183], v[212:215], v[84:87]
	v_mfma_f32_16x16x32_bf16 v[76:79], v[172:175], v[238:241], v[76:79]
	v_mfma_f32_16x16x32_bf16 v[72:75], v[180:183], v[238:241], v[72:75]
	v_mfma_f32_16x16x32_bf16 v[126:129], v[176:179], v[200:203], v[126:129]
	v_mfma_f32_16x16x32_bf16 v[118:121], v[184:187], v[200:203], v[118:121]
	v_mfma_f32_16x16x32_bf16 v[108:111], v[176:179], v[208:211], v[108:111]
	v_mfma_f32_16x16x32_bf16 v[100:103], v[184:187], v[208:211], v[100:103]
	v_mfma_f32_16x16x32_bf16 v[92:95], v[176:179], v[234:237], v[92:95]
	v_mfma_f32_16x16x32_bf16 v[84:87], v[184:187], v[234:237], v[84:87]
	v_mfma_f32_16x16x32_bf16 v[76:79], v[176:179], v[242:245], v[76:79]
	v_mfma_f32_16x16x32_bf16 v[72:75], v[184:187], v[242:245], v[72:75]
	s_setprio 0
	s_barrier
	s_add_i32 s8, s13, s17
	s_add_u32 s100, s92, 0x80
	s_addc_u32 s101, s93, 0
	s_mov_b32 m0, s8
	ds_read_b128 v[188:191], v163 offset:49152
	ds_read_b128 v[200:203], v163 offset:50176
	ds_read_b128 v[204:207], v163 offset:51200
	ds_read_b128 v[208:211], v163 offset:52224
	ds_read_b128 v[212:215], v163 offset:53248
	ds_read_b128 v[234:237], v163 offset:54272
	ds_read_b128 v[238:241], v163 offset:55296
	ds_read_b128 v[242:245], v163 offset:56320
	global_load_lds_dwordx4 v112, s[100:101]
	s_add_i32 m0, s8, 0x2000
	s_add_u32 s8, s92, 0x40080
	v_lshl_add_u64 v[192:193], v[246:247], 0, s[24:25]
	s_addc_u32 s9, s93, 0
	s_add_i32 s13, s31, s17
	global_load_lds_dwordx4 v[192:193], off
	s_nop 0
	s_mov_b32 m0, s13
	s_nop 0
	global_load_lds_dwordx4 v112, s[8:9]
	s_nop 0
	s_add_i32 m0, s13, 0x2000
	s_nop 0
	global_load_lds_dwordx4 v142, s[8:9]
	s_add_u32 s100, s94, 0x80
	s_addc_u32 s101, s95, 0
	s_mov_b32 m0, s36
	s_nop 0
	global_load_lds_dwordx4 v138, s[100:101]
	s_add_u32 s100, s94, 0x80
	s_addc_u32 s101, s95, 0
	s_mov_b32 m0, s37
	s_nop 0
	global_load_lds_dwordx4 v140, s[100:101]
	s_waitcnt vmcnt(8)
	s_waitcnt lgkmcnt(0)
	s_barrier
	s_setprio 1
	s_waitcnt lgkmcnt(0)
	v_mfma_f32_16x16x32_bf16 v[68:71], v[150:153], v[188:191], v[68:71]
	v_mfma_f32_16x16x32_bf16 v[64:67], v[164:167], v[188:191], v[64:67]
	v_mfma_f32_16x16x32_bf16 v[56:59], v[150:153], v[204:207], v[56:59]
	v_mfma_f32_16x16x32_bf16 v[48:51], v[164:167], v[204:207], v[48:51]
	v_mfma_f32_16x16x32_bf16 v[40:43], v[150:153], v[212:215], v[40:43]
	v_mfma_f32_16x16x32_bf16 v[32:35], v[164:167], v[212:215], v[32:35]
	v_mfma_f32_16x16x32_bf16 v[24:27], v[150:153], v[238:241], v[24:27]
	v_mfma_f32_16x16x32_bf16 v[16:19], v[164:167], v[238:241], v[16:19]
	v_mfma_f32_16x16x32_bf16 v[68:71], v[154:157], v[200:203], v[68:71]
	v_mfma_f32_16x16x32_bf16 v[64:67], v[168:171], v[200:203], v[64:67]
	v_mfma_f32_16x16x32_bf16 v[56:59], v[154:157], v[208:211], v[56:59]
	v_mfma_f32_16x16x32_bf16 v[48:51], v[168:171], v[208:211], v[48:51]
	v_mfma_f32_16x16x32_bf16 v[40:43], v[154:157], v[234:237], v[40:43]
	v_mfma_f32_16x16x32_bf16 v[32:35], v[168:171], v[234:237], v[32:35]
	v_mfma_f32_16x16x32_bf16 v[24:27], v[154:157], v[242:245], v[24:27]
	v_mfma_f32_16x16x32_bf16 v[16:19], v[168:171], v[242:245], v[16:19]
	v_mfma_f32_16x16x32_bf16 v[60:63], v[172:175], v[188:191], v[60:63]
	v_mfma_f32_16x16x32_bf16 v[52:55], v[180:183], v[188:191], v[52:55]
	v_mfma_f32_16x16x32_bf16 v[44:47], v[172:175], v[204:207], v[44:47]
	v_mfma_f32_16x16x32_bf16 v[36:39], v[180:183], v[204:207], v[36:39]
	v_mfma_f32_16x16x32_bf16 v[28:31], v[172:175], v[212:215], v[28:31]
	v_mfma_f32_16x16x32_bf16 v[20:23], v[180:183], v[212:215], v[20:23]
	v_mfma_f32_16x16x32_bf16 v[12:15], v[172:175], v[238:241], v[12:15]
	v_mfma_f32_16x16x32_bf16 v[8:11], v[180:183], v[238:241], v[8:11]
	v_mfma_f32_16x16x32_bf16 v[60:63], v[176:179], v[200:203], v[60:63]
	v_mfma_f32_16x16x32_bf16 v[52:55], v[184:187], v[200:203], v[52:55]
	v_mfma_f32_16x16x32_bf16 v[44:47], v[176:179], v[208:211], v[44:47]
	v_mfma_f32_16x16x32_bf16 v[36:39], v[184:187], v[208:211], v[36:39]
	v_mfma_f32_16x16x32_bf16 v[28:31], v[176:179], v[234:237], v[28:31]
	v_mfma_f32_16x16x32_bf16 v[20:23], v[184:187], v[234:237], v[20:23]
	v_mfma_f32_16x16x32_bf16 v[12:15], v[176:179], v[242:245], v[12:15]
	v_mfma_f32_16x16x32_bf16 v[8:11], v[184:187], v[242:245], v[8:11]
	s_setprio 0
	s_barrier
	s_add_i32 s97, s97, 2
	s_add_u32 s42, s42, 0x100
	s_addc_u32 s43, s43, 0
	s_add_u32 vcc_hi, vcc_hi, 0x100
	s_addc_u32 s96, s96, 0
	s_cmp_gt_u32 s97, 13
	s_cbranch_scc0 .LBB0_356
	s_and_b64 vcc, exec, s[80:81]
	s_cbranch_vccz .LBB0_359
	s_barrier
; __device__ __forceinline__ u32x4 pack8(f32x4 a, f32x4 b) { u32x4 w; w.x = cvt_pk_bf16(a[0], a[1]); w.y = cvt_pk_bf16(a[2], a[3]); w.z = cvt_pk_bf16(b[0], b[1]); w.w = cvt_pk_bf16(b[2], b[3]); return w; }
;     __device__ __forceinline__ void operator()(const f32x4 (&acc)[2][2][4][2], const Unit& u, int wr, int wc, int fr_, int fq_, int slot) const {
;         int fr = fr_, fq = fq_; asm volatile("" : "+v"(fr), "+v"(fq));
;         const int pn = u.pn;
;         const int col0 = pn * BM + wc * 32 + 8 * fq;
;         float rs[2][4];
; #pragma unroll
;         for (int ai = 0; ai < 2; ++ai)
; #pragma unroll
;             for (int m = 0; m < 4; ++m) rs[ai][m] = rst[slot * 256 + ai * HALF + wr * 64 + m * 16 + fr];
; #pragma unroll
;         for (int ai = 0; ai < 2; ++ai)
; #pragma unroll
;             for (int m = 0; m < 4; ++m) {
;                 bf16_t* rowp = P + (size_t)(u.pm * BM + ai * HALF + wr * 64 + m * 16 + fr) * EVEN_IN + col0;
; #pragma unroll
;                 for (int bj = 0; bj < 2; ++bj) {
;                     f32x4 v0 = acc[ai][bj][m][0] * rs[ai][m], v1 = acc[ai][bj][m][1] * rs[ai][m];
;                     *(u32x4*)(rowp + bj * HALF) = pack8(v0, v1);
;                 }
;                 asm volatile("" ::: "memory");
;             }
;     }
.LBB0_359:
	v_cndmask_b32_e64 v150, 0, 1, s[40:41]
	v_readlane_b32 s96, v255, 45
	v_cmp_ne_u32_e64 s[42:43], 1, v150
	s_andn2_b64 vcc, exec, s[40:41]
	v_readlane_b32 s97, v255, 46
	s_cbranch_vccnz .LBB0_361
	s_lshl_b64 s[8:9], s[84:85], 14
.LBB0_361:
	s_lshl_b32 s8, s91, 10
	s_and_b32 s8, s8, 0x400
	v_mov_b32_e32 v152, v160
	v_mov_b32_e32 v153, v159
	v_lshrrev_b32_e32 v200, 2, v159
	v_lshl_add_u32 v200, v160, 2, v200
	v_and_b32_e32 v201, 3, v159
	v_lshrrev_b32_e32 v202, 6, v233
	v_lshlrev_b32_e32 v202, 11, v202
	v_add_u32_e32 v202, 0x20000, v202
	v_mul_u32_u24_e32 v203, 0x50, v159
	v_lshl_add_u32 v203, v160, 4, v203
	v_add_u32_e32 v203, v203, v202
	v_mul_u32_u24_e32 v204, 0x50, v200
	v_lshl_add_u32 v204, v201, 4, v204
	v_add_u32_e32 v204, v204, v202
	s_add_i32 s8, s46, s8
	s_movk_i32 s13, 0x1200
	v_lshl_add_u32 v150, v153, 2, s8
	s_lshl_b32 s8, s22, 8
	s_or_b32 s8, s8, s35
	v_lshl_add_u32 v154, v201, 3, s8
	s_lshl_b32 s8, s90, 8
	s_add_i32 s8, s8, s33
	ds_read2_b32 v[164:165], v150 offset1:16
	ds_read2_b32 v[166:167], v150 offset0:32 offset1:48
	ds_read2_b32 v[156:157], v150 offset0:128 offset1:144
	ds_read2_b32 v[150:151], v150 offset0:160 offset1:176
	v_add_u32_e32 v172, s8, v200
	v_ashrrev_i32_e32 v155, 31, v154
	v_mov_b64_e32 v[152:153], s[0:1]
	v_mad_i64_i32 v[168:169], s[8:9], v172, s13, v[152:153]
	v_lshlrev_b64 v[154:155], 1, v[154:155]
	v_lshl_add_u64 v[168:169], v[168:169], 0, v[154:155]
	s_waitcnt lgkmcnt(0)
	v_pk_mul_f32 v[136:137], v[136:137], v[164:165] op_sel_hi:[1,0]
	v_pk_mul_f32 v[134:135], v[134:135], v[164:165] op_sel_hi:[1,0]
	v_pk_mul_f32 v[170:171], v[132:133], v[164:165] op_sel_hi:[1,0]
	v_pk_mul_f32 v[132:133], v[130:131], v[164:165] op_sel_hi:[1,0]
	v_cvt_pk_bf16_f32 v130, v134, v135
	v_cvt_pk_bf16_f32 v131, v136, v137
	v_pk_mul_f32 v[126:127], v[126:127], v[164:165] op_sel_hi:[1,0]
	v_cvt_pk_bf16_f32 v132, v132, v133
	v_cvt_pk_bf16_f32 v133, v170, v171
	ds_write_b128 v203, v[130:133]
	ds_read_b128 v[130:133], v204
	s_waitcnt lgkmcnt(0)
	global_store_dwordx4 v[168:169], v[130:133], off
	v_pk_mul_f32 v[128:129], v[128:129], v[164:165] op_sel_hi:[1,0]
	v_pk_mul_f32 v[104:105], v[104:105], v[166:167] op_sel_hi:[1,0]
	v_pk_mul_f32 v[130:131], v[120:121], v[164:165] op_sel_hi:[1,0]
	v_pk_mul_f32 v[120:121], v[118:119], v[164:165] op_sel_hi:[1,0]
	v_cvt_pk_bf16_f32 v118, v126, v127
	v_cvt_pk_bf16_f32 v119, v128, v129
	v_pk_mul_f32 v[92:93], v[92:93], v[166:167] op_sel_hi:[1,0]
	v_cvt_pk_bf16_f32 v120, v120, v121
	v_cvt_pk_bf16_f32 v121, v130, v131
	ds_write_b128 v203, v[118:121]
	ds_read_b128 v[118:121], v204
	s_waitcnt lgkmcnt(0)
	global_store_dwordx4 v[168:169], v[118:121], off offset:256
	v_pk_mul_f32 v[94:95], v[94:95], v[166:167] op_sel_hi:[1,0]
	v_pk_mul_f32 v[70:71], v[70:71], v[156:157] op_sel_hi:[1,0]
	v_add_u32_e32 v118, 16, v172
	v_mad_i64_i32 v[118:119], s[8:9], v118, s13, v[152:153]
	v_mov_b32_e32 v120, v165
	v_lshl_add_u64 v[118:119], v[118:119], 0, v[154:155]
	v_pk_mul_f32 v[124:125], v[124:125], v[120:121] op_sel_hi:[1,0]
	v_pk_mul_f32 v[122:123], v[122:123], v[120:121] op_sel_hi:[1,0]
	v_pk_mul_f32 v[126:127], v[116:117], v[120:121] op_sel_hi:[1,0]
	v_pk_mul_f32 v[116:117], v[114:115], v[120:121] op_sel_hi:[1,0]
	v_cvt_pk_bf16_f32 v114, v122, v123
	v_cvt_pk_bf16_f32 v115, v124, v125
	v_pk_mul_f32 v[108:109], v[108:109], v[120:121] op_sel_hi:[1,0]
	v_cvt_pk_bf16_f32 v116, v116, v117
	v_cvt_pk_bf16_f32 v117, v126, v127
	ds_write_b128 v203, v[114:117]
	ds_read_b128 v[114:117], v204
	s_waitcnt lgkmcnt(0)
	global_store_dwordx4 v[118:119], v[114:117], off
	v_pk_mul_f32 v[110:111], v[110:111], v[120:121] op_sel_hi:[1,0]
	v_pk_mul_f32 v[68:69], v[68:69], v[156:157] op_sel_hi:[1,0]
	v_pk_mul_f32 v[114:115], v[102:103], v[120:121] op_sel_hi:[1,0]
	v_pk_mul_f32 v[102:103], v[100:101], v[120:121] op_sel_hi:[1,0]
	v_cvt_pk_bf16_f32 v100, v108, v109
	v_cvt_pk_bf16_f32 v101, v110, v111
	v_pk_mul_f32 v[60:61], v[60:61], v[156:157] op_sel_hi:[1,0]
	v_cvt_pk_bf16_f32 v102, v102, v103
	v_cvt_pk_bf16_f32 v103, v114, v115
	ds_write_b128 v203, v[100:103]
	ds_read_b128 v[100:103], v204
	s_waitcnt lgkmcnt(0)
	global_store_dwordx4 v[118:119], v[100:103], off offset:256
	v_pk_mul_f32 v[62:63], v[62:63], v[156:157] op_sel_hi:[1,0]
	v_pk_mul_f32 v[40:41], v[40:41], v[150:151] op_sel_hi:[1,0]
	v_add_u32_e32 v100, 32, v172
	v_mad_i64_i32 v[100:101], s[8:9], v100, s13, v[152:153]
	v_lshl_add_u64 v[100:101], v[100:101], 0, v[154:155]
	v_pk_mul_f32 v[102:103], v[106:107], v[166:167] op_sel_hi:[1,0]
	v_pk_mul_f32 v[106:107], v[98:99], v[166:167] op_sel_hi:[1,0]
	v_pk_mul_f32 v[98:99], v[96:97], v[166:167] op_sel_hi:[1,0]
	v_cvt_pk_bf16_f32 v96, v104, v105
	v_cvt_pk_bf16_f32 v97, v102, v103
	v_pk_mul_f32 v[28:29], v[28:29], v[150:151] op_sel_hi:[1,0]
	v_cvt_pk_bf16_f32 v98, v98, v99
	v_cvt_pk_bf16_f32 v99, v106, v107
	ds_write_b128 v203, v[96:99]
	ds_read_b128 v[96:99], v204
	s_waitcnt lgkmcnt(0)
	global_store_dwordx4 v[100:101], v[96:99], off
	v_pk_mul_f32 v[30:31], v[30:31], v[150:151] op_sel_hi:[1,0]
	s_and_b64 vcc, exec, s[42:43]
	v_pk_mul_f32 v[96:97], v[86:87], v[166:167] op_sel_hi:[1,0]
	v_pk_mul_f32 v[86:87], v[84:85], v[166:167] op_sel_hi:[1,0]
	v_cvt_pk_bf16_f32 v84, v92, v93
	v_cvt_pk_bf16_f32 v85, v94, v95
	s_mov_b64 s[40:41], -1
	v_cvt_pk_bf16_f32 v86, v86, v87
	v_cvt_pk_bf16_f32 v87, v96, v97
	ds_write_b128 v203, v[84:87]
	ds_read_b128 v[84:87], v204
	s_waitcnt lgkmcnt(0)
; __device__ __forceinline__ u32x4 pack8(f32x4 a, f32x4 b) { u32x4 w; w.x = cvt_pk_bf16(a[0], a[1]); w.y = cvt_pk_bf16(a[2], a[3]); w.z = cvt_pk_bf16(b[0], b[1]); w.w = cvt_pk_bf16(b[2], b[3]); return w; }
;     __device__ __forceinline__ void operator()(const f32x4 (&acc)[2][2][4][2], const Unit& u, int wr, int wc, int fr_, int fq_, int slot) const {
;         int fr = fr_, fq = fq_; asm volatile("" : "+v"(fr), "+v"(fq));
;         const int pn = u.pn;
;         const int col0 = pn * BM + wc * 32 + 8 * fq;
;         float rs[2][4];
; #pragma unroll
;         for (int ai = 0; ai < 2; ++ai)
; #pragma unroll
;             for (int m = 0; m < 4; ++m) rs[ai][m] = rst[slot * 256 + ai * HALF + wr * 64 + m * 16 + fr];
; #pragma unroll
;         for (int ai = 0; ai < 2; ++ai)
; #pragma unroll
;             for (int m = 0; m < 4; ++m) {
;                 bf16_t* rowp = P + (size_t)(u.pm * BM + ai * HALF + wr * 64 + m * 16 + fr) * EVEN_IN + col0;
; #pragma unroll
;                 for (int bj = 0; bj < 2; ++bj) {
;                     f32x4 v0 = acc[ai][bj][m][0] * rs[ai][m], v1 = acc[ai][bj][m][1] * rs[ai][m];
;                     *(u32x4*)(rowp + bj * HALF) = pack8(v0, v1);
;                 }
;                 asm volatile("" ::: "memory");
;             }
;     }
	global_store_dwordx4 v[100:101], v[84:87], off offset:256
	s_nop 1
	v_add_u32_e32 v84, 48, v172
	v_mad_i64_i32 v[84:85], s[8:9], v84, s13, v[152:153]
	v_mov_b32_e32 v86, v167
	v_lshl_add_u64 v[84:85], v[84:85], 0, v[154:155]
	v_pk_mul_f32 v[90:91], v[90:91], v[86:87] op_sel_hi:[1,0]
	v_pk_mul_f32 v[88:89], v[88:89], v[86:87] op_sel_hi:[1,0]
	v_pk_mul_f32 v[92:93], v[82:83], v[86:87] op_sel_hi:[1,0]
	v_pk_mul_f32 v[82:83], v[80:81], v[86:87] op_sel_hi:[1,0]
	v_cvt_pk_bf16_f32 v80, v88, v89
	v_cvt_pk_bf16_f32 v81, v90, v91
	v_pk_mul_f32 v[76:77], v[76:77], v[86:87] op_sel_hi:[1,0]
	v_cvt_pk_bf16_f32 v82, v82, v83
	v_cvt_pk_bf16_f32 v83, v92, v93
	ds_write_b128 v203, v[80:83]
	ds_read_b128 v[80:83], v204
	s_waitcnt lgkmcnt(0)
	global_store_dwordx4 v[84:85], v[80:83], off
	v_pk_mul_f32 v[78:79], v[78:79], v[86:87] op_sel_hi:[1,0]
	s_nop 0
	v_pk_mul_f32 v[80:81], v[74:75], v[86:87] op_sel_hi:[1,0]
	v_pk_mul_f32 v[74:75], v[72:73], v[86:87] op_sel_hi:[1,0]
	v_cvt_pk_bf16_f32 v72, v76, v77
	v_cvt_pk_bf16_f32 v73, v78, v79
	s_nop 0
	v_cvt_pk_bf16_f32 v74, v74, v75
	v_cvt_pk_bf16_f32 v75, v80, v81
	ds_write_b128 v203, v[72:75]
	ds_read_b128 v[72:75], v204
	s_waitcnt lgkmcnt(0)
	global_store_dwordx4 v[84:85], v[72:75], off offset:256
	s_nop 1
	v_add_u32_e32 v72, 0x80, v172
	v_mad_i64_i32 v[72:73], s[8:9], v72, s13, v[152:153]
	v_lshl_add_u64 v[72:73], v[72:73], 0, v[154:155]
	v_pk_mul_f32 v[74:75], v[66:67], v[156:157] op_sel_hi:[1,0]
	v_pk_mul_f32 v[66:67], v[64:65], v[156:157] op_sel_hi:[1,0]
	v_cvt_pk_bf16_f32 v64, v68, v69
	v_cvt_pk_bf16_f32 v65, v70, v71
	s_nop 0
	v_cvt_pk_bf16_f32 v66, v66, v67
	v_cvt_pk_bf16_f32 v67, v74, v75
	ds_write_b128 v203, v[64:67]
	ds_read_b128 v[64:67], v204
	s_waitcnt lgkmcnt(0)
	global_store_dwordx4 v[72:73], v[64:67], off
	s_nop 1
	v_pk_mul_f32 v[64:65], v[54:55], v[156:157] op_sel_hi:[1,0]
	v_pk_mul_f32 v[54:55], v[52:53], v[156:157] op_sel_hi:[1,0]
	v_cvt_pk_bf16_f32 v52, v60, v61
	v_cvt_pk_bf16_f32 v53, v62, v63
	s_nop 0
	v_cvt_pk_bf16_f32 v54, v54, v55
	v_cvt_pk_bf16_f32 v55, v64, v65
	ds_write_b128 v203, v[52:55]
	ds_read_b128 v[52:55], v204
	s_waitcnt lgkmcnt(0)
	global_store_dwordx4 v[72:73], v[52:55], off offset:256
	s_nop 1
	v_add_u32_e32 v52, 0x90, v172
	v_mad_i64_i32 v[52:53], s[8:9], v52, s13, v[152:153]
	v_mov_b32_e32 v54, v157
	v_lshl_add_u64 v[52:53], v[52:53], 0, v[154:155]
	v_pk_mul_f32 v[58:59], v[58:59], v[54:55] op_sel_hi:[1,0]
	v_pk_mul_f32 v[56:57], v[56:57], v[54:55] op_sel_hi:[1,0]
	v_pk_mul_f32 v[60:61], v[50:51], v[54:55] op_sel_hi:[1,0]
	v_pk_mul_f32 v[50:51], v[48:49], v[54:55] op_sel_hi:[1,0]
	v_cvt_pk_bf16_f32 v48, v56, v57
	v_cvt_pk_bf16_f32 v49, v58, v59
	v_pk_mul_f32 v[44:45], v[44:45], v[54:55] op_sel_hi:[1,0]
	v_cvt_pk_bf16_f32 v50, v50, v51
	v_cvt_pk_bf16_f32 v51, v60, v61
	ds_write_b128 v203, v[48:51]
	ds_read_b128 v[48:51], v204
	s_waitcnt lgkmcnt(0)
	global_store_dwordx4 v[52:53], v[48:51], off
	v_pk_mul_f32 v[46:47], v[46:47], v[54:55] op_sel_hi:[1,0]
	s_nop 0
	v_pk_mul_f32 v[48:49], v[38:39], v[54:55] op_sel_hi:[1,0]
	v_pk_mul_f32 v[38:39], v[36:37], v[54:55] op_sel_hi:[1,0]
	v_cvt_pk_bf16_f32 v36, v44, v45
	v_cvt_pk_bf16_f32 v37, v46, v47
	s_nop 0
	v_cvt_pk_bf16_f32 v38, v38, v39
	v_cvt_pk_bf16_f32 v39, v48, v49
	ds_write_b128 v203, v[36:39]
	ds_read_b128 v[36:39], v204
	s_waitcnt lgkmcnt(0)
	global_store_dwordx4 v[52:53], v[36:39], off offset:256
	s_nop 1
	v_add_u32_e32 v36, 0xa0, v172
	v_mad_i64_i32 v[36:37], s[8:9], v36, s13, v[152:153]
	v_lshl_add_u64 v[36:37], v[36:37], 0, v[154:155]
	v_pk_mul_f32 v[38:39], v[42:43], v[150:151] op_sel_hi:[1,0]
	v_pk_mul_f32 v[42:43], v[34:35], v[150:151] op_sel_hi:[1,0]
	v_pk_mul_f32 v[34:35], v[32:33], v[150:151] op_sel_hi:[1,0]
	v_cvt_pk_bf16_f32 v32, v40, v41
	v_cvt_pk_bf16_f32 v33, v38, v39
	s_nop 0
	v_cvt_pk_bf16_f32 v34, v34, v35
	v_cvt_pk_bf16_f32 v35, v42, v43
	ds_write_b128 v203, v[32:35]
	ds_read_b128 v[32:35], v204
	s_waitcnt lgkmcnt(0)
	global_store_dwordx4 v[36:37], v[32:35], off
	s_nop 1
	v_pk_mul_f32 v[32:33], v[22:23], v[150:151] op_sel_hi:[1,0]
	v_pk_mul_f32 v[22:23], v[20:21], v[150:151] op_sel_hi:[1,0]
	v_cvt_pk_bf16_f32 v20, v28, v29
	v_cvt_pk_bf16_f32 v21, v30, v31
	s_nop 0
	v_cvt_pk_bf16_f32 v22, v22, v23
	v_cvt_pk_bf16_f32 v23, v32, v33
	ds_write_b128 v203, v[20:23]
	ds_read_b128 v[20:23], v204
	s_waitcnt lgkmcnt(0)
	global_store_dwordx4 v[36:37], v[20:23], off offset:256
	s_nop 1
	v_add_u32_e32 v20, 0xb0, v172
	v_mad_i64_i32 v[20:21], s[8:9], v20, s13, v[152:153]
	v_mov_b32_e32 v22, v151
	v_lshl_add_u64 v[20:21], v[20:21], 0, v[154:155]
	v_pk_mul_f32 v[26:27], v[26:27], v[22:23] op_sel_hi:[1,0]
	v_pk_mul_f32 v[24:25], v[24:25], v[22:23] op_sel_hi:[1,0]
	v_pk_mul_f32 v[28:29], v[18:19], v[22:23] op_sel_hi:[1,0]
	v_pk_mul_f32 v[18:19], v[16:17], v[22:23] op_sel_hi:[1,0]
	v_cvt_pk_bf16_f32 v16, v24, v25
	v_cvt_pk_bf16_f32 v17, v26, v27
	v_pk_mul_f32 v[14:15], v[14:15], v[22:23] op_sel_hi:[1,0]
	v_cvt_pk_bf16_f32 v18, v18, v19
	v_cvt_pk_bf16_f32 v19, v28, v29
	ds_write_b128 v203, v[16:19]
	ds_read_b128 v[16:19], v204
	s_waitcnt lgkmcnt(0)
	global_store_dwordx4 v[20:21], v[16:19], off
	v_pk_mul_f32 v[12:13], v[12:13], v[22:23] op_sel_hi:[1,0]
	v_readlane_b32 s13, v255, 49
	v_pk_mul_f32 v[16:17], v[10:11], v[22:23] op_sel_hi:[1,0]
	v_pk_mul_f32 v[10:11], v[8:9], v[22:23] op_sel_hi:[1,0]
	v_cvt_pk_bf16_f32 v8, v12, v13
	v_cvt_pk_bf16_f32 v9, v14, v15
	s_nop 0
	v_cvt_pk_bf16_f32 v10, v10, v11
	v_cvt_pk_bf16_f32 v11, v16, v17
	ds_write_b128 v203, v[8:11]
	ds_read_b128 v[8:11], v204
	s_waitcnt lgkmcnt(0)
	global_store_dwordx4 v[20:21], v[8:11], off offset:256
	s_cmp_lg_u32 s22, 6
	s_cbranch_scc1 .Lkp_skip
; __device__ __forceinline__ unsigned cvt_pk_bf16(float lo, float hi) { unsigned r; asm volatile("v_cvt_pk_bf16_f32 %0, %1, %2" : "=v"(r) : "v"(lo), "v"(hi)); return r; }
; __device__ __forceinline__ void kprep_item(bf16_t* P, const float* kg, const float* rope, int idx, const u32x4 w) {
;     const int e8 = idx & 7, hk = (idx >> 3) & 1, row = idx >> 4;
;     float x[8] = {bflo(w.x), bfhi(w.x), bflo(w.y), bfhi(w.y), bflo(w.z), bfhi(w.z), bflo(w.w), bfhi(w.w)};
;     float ssq = 0.f;
; #pragma unroll
;     for (int e = 0; e < 8; ++e) ssq += x[e] * x[e];
;     ssq += __shfl_xor(ssq, 1); ssq += __shfl_xor(ssq, 2); ssq += __shfl_xor(ssq, 4);
;     const float rh = __builtin_amdgcn_rsqf(ssq * (1.0f / 64.0f) + EPS);
;     const int t = row & (SEQ - 1), ir = (e8 < 4) ? (t >> 6) : (t & 63), f0 = 8 * (e8 & 1);
;     const f32x4 g0 = *(const f32x4*)(kg + e8 * 8), g1 = *(const f32x4*)(kg + e8 * 8 + 4);
;     const f32x4 c0 = *(const f32x4*)(rope + ir * 16 + f0), c1 = *(const f32x4*)(rope + ir * 16 + f0 + 4);
;     const f32x4 s0 = *(const f32x4*)(rope + 1024 + ir * 16 + f0), s1 = *(const f32x4*)(rope + 1024 + ir * 16 + f0 + 4);
;     const float sgn = (e8 & 2) ? 1.0f : -1.0f;
;     float o[8];
; #pragma unroll
;     for (int e = 0; e < 8; ++e) {
;         const float y = x[e] * rh * (e < 4 ? g0[e & 3] : g1[e & 3]);
;         const float other = __shfl_xor(y, 2);
;         o[e] = y * (e < 4 ? c0[e & 3] : c1[e & 3]) + sgn * other * (e < 4 ? s0[e & 3] : s1[e & 3]);
;     }
;     u32x4 r; r.x = cvt_pk_bf16(o[0], o[1]); r.y = cvt_pk_bf16(o[2], o[3]); r.z = cvt_pk_bf16(o[4], o[5]); r.w = cvt_pk_bf16(o[6], o[7]);
;     *(u32x4*)(P + (size_t)row * EVEN_IN + 1536 + hk * 64 + e8 * 8) = r;
; }
; __device__ __forceinline__ void kprep_phase(bf16_t* P, const float* kg, const float* rope, int tid, int bx, int G) {
;     const int stride = G * 512;
;     for (int base = bx * 512 + tid; base < MTOK * 16; base += 3 * stride) {
;         u32x4 w[3];
; #pragma unroll
;         for (int q = 0; q < 3; ++q) { const int idx = base + q * stride; if (idx < MTOK * 16) w[q] = *(const u32x4*)(P + (size_t)(idx >> 4) * EVEN_IN + 1536 + ((idx >> 3) & 1) * 64 + (idx & 7) * 8); }
; #pragma unroll
;         for (int q = 0; q < 3; ++q) { const int idx = base + q * stride; if (idx < MTOK * 16) kprep_item(P, kg, rope, idx, w[q]); }
;     }
	s_waitcnt vmcnt(0)
	s_barrier
	v_and_b32_e32 v30, 7, v233
	v_bfe_u32 v31, v233, 3, 1
	v_lshrrev_b32_e32 v32, 4, v233
	s_lshl_b32 s8, s90, 8
	v_add_u32_e32 v32, s8, v32
	v_lshlrev_b32_e32 v33, 7, v31
	v_lshl_add_u32 v33, v30, 4, v33
	v_mul_u32_u24_e32 v36, 0x1200, v32
	v_add_u32_e32 v36, v36, v33
	v_mov_b32_e32 v37, v36
	global_load_dwordx4 v[48:51], v37, s[0:1] offset:3072 sc1
	v_add_u32_e32 v37, 0x24000, v37
	global_load_dwordx4 v[52:55], v37, s[0:1] offset:3072 sc1
	v_add_u32_e32 v37, 0x24000, v37
	global_load_dwordx4 v[56:59], v37, s[0:1] offset:3072 sc1
	v_add_u32_e32 v37, 0x24000, v37
	global_load_dwordx4 v[60:63], v37, s[0:1] offset:3072 sc1
	v_add_u32_e32 v37, 0x24000, v37
	global_load_dwordx4 v[64:67], v37, s[0:1] offset:3072 sc1
	v_add_u32_e32 v37, 0x24000, v37
	global_load_dwordx4 v[68:71], v37, s[0:1] offset:3072 sc1
	v_add_u32_e32 v37, 0x24000, v37
	global_load_dwordx4 v[72:75], v37, s[0:1] offset:3072 sc1
	v_add_u32_e32 v37, 0x24000, v37
	global_load_dwordx4 v[76:79], v37, s[0:1] offset:3072 sc1
	v_readlane_b32 s8, v255, 49
	s_nop 3
	s_add_i32 s8, s8, -1
	s_lshr_b32 s8, s8, 3
	s_lshl_b32 s8, s8, 8
	v_mov_b32_e32 v131, 0
	v_lshlrev_b32_e32 v130, 5, v30
	v_add_u32_e32 v130, s8, v130
	v_lshl_add_u64 v[244:245], s[62:63], 0, v[130:131]
	global_load_dwordx4 v[40:43], v[244:245], off
	global_load_dwordx4 v[44:47], v[244:245], off offset:16
	v_readlane_b32 s8, v253, 8
	v_readlane_b32 s9, v253, 9
	v_and_b32_e32 v38, 1, v30
	v_lshlrev_b32_e32 v38, 5, v38
	v_and_b32_e32 v39, 2, v30
	v_lshlrev_b32_e32 v39, 30, v39
	v_xor_b32_e32 v39, 0xbf800000, v39
	v_cmp_gt_u32_e32 vcc, 4, v30
	s_nop 3
	v_mov_b32_e32 v34, v32
	v_and_b32_e32 v35, 0xfff, v34
	v_lshrrev_b32_e32 v242, 6, v35
	v_and_b32_e32 v243, 63, v35
	v_cndmask_b32_e32 v242, v243, v242, vcc
	v_lshl_add_u32 v130, v242, 6, v38
	v_lshl_add_u64 v[244:245], s[8:9], 0, v[130:131]
	global_load_dwordx4 v[80:83], v[244:245], off
	global_load_dwordx4 v[84:87], v[244:245], off offset:16
	v_add_u32_e32 v130, 0x1000, v130
	v_lshl_add_u64 v[244:245], s[8:9], 0, v[130:131]
	global_load_dwordx4 v[88:91], v[244:245], off
	global_load_dwordx4 v[92:95], v[244:245], off offset:16
	v_add_u32_e32 v34, 32, v34
	v_and_b32_e32 v35, 0xfff, v34
	v_lshrrev_b32_e32 v242, 6, v35
	v_and_b32_e32 v243, 63, v35
	v_cndmask_b32_e32 v242, v243, v242, vcc
	v_lshl_add_u32 v130, v242, 6, v38
	v_lshl_add_u64 v[244:245], s[8:9], 0, v[130:131]
	global_load_dwordx4 v[96:99], v[244:245], off
	global_load_dwordx4 v[100:103], v[244:245], off offset:16
	v_add_u32_e32 v130, 0x1000, v130
	v_lshl_add_u64 v[244:245], s[8:9], 0, v[130:131]
	global_load_dwordx4 v[104:107], v[244:245], off
	global_load_dwordx4 v[108:111], v[244:245], off offset:16
	v_add_u32_e32 v34, 32, v34
	v_and_b32_e32 v35, 0xfff, v34
	v_lshrrev_b32_e32 v242, 6, v35
	v_and_b32_e32 v243, 63, v35
	v_cndmask_b32_e32 v242, v243, v242, vcc
	v_lshl_add_u32 v130, v242, 6, v38
	v_lshl_add_u64 v[244:245], s[8:9], 0, v[130:131]
	global_load_dwordx4 v[114:117], v[244:245], off
	global_load_dwordx4 v[118:121], v[244:245], off offset:16
	v_add_u32_e32 v130, 0x1000, v130
	v_lshl_add_u64 v[244:245], s[8:9], 0, v[130:131]
	global_load_dwordx4 v[122:125], v[244:245], off
	global_load_dwordx4 v[126:129], v[244:245], off offset:16
	s_waitcnt vmcnt(12)
	s_waitcnt vmcnt(8)
	v_lshlrev_b32_e32 v200, 16, v48
	v_and_b32_e32 v201, 0xffff0000, v48
	v_lshlrev_b32_e32 v202, 16, v49
	v_and_b32_e32 v203, 0xffff0000, v49
	v_lshlrev_b32_e32 v204, 16, v50
	v_and_b32_e32 v205, 0xffff0000, v50
	v_lshlrev_b32_e32 v206, 16, v51
	v_and_b32_e32 v207, 0xffff0000, v51
	v_mul_f32_e32 v234, v200, v200
	v_fmac_f32_e32 v234, v201, v201
	v_fmac_f32_e32 v234, v202, v202
	v_fmac_f32_e32 v234, v203, v203
	v_fmac_f32_e32 v234, v204, v204
	v_fmac_f32_e32 v234, v205, v205
	v_fmac_f32_e32 v234, v206, v206
	v_fmac_f32_e32 v234, v207, v207
	s_nop 1
	v_add_f32_dpp v235, v234, v234 quad_perm:[1,0,3,2] row_mask:0xf bank_mask:0xf
	s_nop 1
	v_add_f32_dpp v234, v235, v235 quad_perm:[2,3,0,1] row_mask:0xf bank_mask:0xf
	s_nop 1
	v_add_f32_dpp v235, v234, v234 row_half_mirror row_mask:0xf bank_mask:0xf
	v_fmamk_f32 v235, v235, 0x3c800000, v217
	v_rsq_f32_e32 v235, v235
	s_nop 0
	v_mul_f32_e32 v200, v200, v235
	v_mul_f32_e32 v201, v201, v235
	v_mul_f32_e32 v202, v202, v235
	v_mul_f32_e32 v203, v203, v235
	v_mul_f32_e32 v204, v204, v235
	v_mul_f32_e32 v205, v205, v235
	v_mul_f32_e32 v206, v206, v235
	v_mul_f32_e32 v207, v207, v235
	v_mul_f32_e32 v200, v200, v40
	v_mul_f32_e32 v201, v201, v41
	v_mul_f32_e32 v202, v202, v42
	v_mul_f32_e32 v203, v203, v43
	v_mul_f32_e32 v204, v204, v44
	v_mul_f32_e32 v205, v205, v45
	v_mul_f32_e32 v206, v206, v46
	v_mul_f32_e32 v207, v207, v47
	s_nop 1
	v_mov_b32_dpp v208, v200 quad_perm:[2,3,0,1] row_mask:0xf bank_mask:0xf
	v_mov_b32_dpp v209, v201 quad_perm:[2,3,0,1] row_mask:0xf bank_mask:0xf
	v_mov_b32_dpp v210, v202 quad_perm:[2,3,0,1] row_mask:0xf bank_mask:0xf
	v_mov_b32_dpp v211, v203 quad_perm:[2,3,0,1] row_mask:0xf bank_mask:0xf
	v_mov_b32_dpp v212, v204 quad_perm:[2,3,0,1] row_mask:0xf bank_mask:0xf
	v_mov_b32_dpp v213, v205 quad_perm:[2,3,0,1] row_mask:0xf bank_mask:0xf
	v_mov_b32_dpp v214, v206 quad_perm:[2,3,0,1] row_mask:0xf bank_mask:0xf
	v_mov_b32_dpp v215, v207 quad_perm:[2,3,0,1] row_mask:0xf bank_mask:0xf
	v_mul_f32_e32 v208, v39, v208
	v_mul_f32_e32 v209, v39, v209
	v_mul_f32_e32 v210, v39, v210
	v_mul_f32_e32 v211, v39, v211
	v_mul_f32_e32 v212, v39, v212
	v_mul_f32_e32 v213, v39, v213
	v_mul_f32_e32 v214, v39, v214
	v_mul_f32_e32 v215, v39, v215
	v_mul_f32_e32 v208, v208, v88
	v_mul_f32_e32 v209, v209, v89
	v_mul_f32_e32 v210, v210, v90
	v_mul_f32_e32 v211, v211, v91
	v_mul_f32_e32 v212, v212, v92
	v_mul_f32_e32 v213, v213, v93
	v_mul_f32_e32 v214, v214, v94
	v_mul_f32_e32 v215, v215, v95
	v_fma_f32 v200, v200, v80, v208
	v_fma_f32 v201, v201, v81, v209
	v_fma_f32 v202, v202, v82, v210
	v_fma_f32 v203, v203, v83, v211
	v_fma_f32 v204, v204, v84, v212
	v_fma_f32 v205, v205, v85, v213
	v_fma_f32 v206, v206, v86, v214
	v_fma_f32 v207, v207, v87, v215
	v_cvt_pk_bf16_f32 v240, v200, v201
	v_cvt_pk_bf16_f32 v241, v202, v203
	v_cvt_pk_bf16_f32 v242, v204, v205
	v_cvt_pk_bf16_f32 v243, v206, v207
	v_mov_b32_e32 v37, v36
	global_store_dwordx4 v37, v[240:243], s[0:1] offset:3072
	v_add_u32_e32 v34, 32, v34
	v_and_b32_e32 v35, 0xfff, v34
	v_lshrrev_b32_e32 v242, 6, v35
	v_and_b32_e32 v243, 63, v35
	v_cndmask_b32_e32 v242, v243, v242, vcc
	v_lshl_add_u32 v130, v242, 6, v38
	v_lshl_add_u64 v[244:245], s[8:9], 0, v[130:131]
	global_load_dwordx4 v[80:83], v[244:245], off
	global_load_dwordx4 v[84:87], v[244:245], off offset:16
	v_add_u32_e32 v130, 0x1000, v130
	v_lshl_add_u64 v[244:245], s[8:9], 0, v[130:131]
	global_load_dwordx4 v[88:91], v[244:245], off
	global_load_dwordx4 v[92:95], v[244:245], off offset:16
	s_waitcnt vmcnt(9)
; __device__ __forceinline__ unsigned cvt_pk_bf16(float lo, float hi) { unsigned r; asm volatile("v_cvt_pk_bf16_f32 %0, %1, %2" : "=v"(r) : "v"(lo), "v"(hi)); return r; }
; __device__ __forceinline__ float bflo(unsigned w) { return __uint_as_float(w << 16); }
; __device__ __forceinline__ float bfhi(unsigned w) { return __uint_as_float(w & 0xffff0000u); }
; __device__ __forceinline__ void kprep_item(bf16_t* P, const float* kg, const float* rope, int idx, const u32x4 w) {
;     const int e8 = idx & 7, hk = (idx >> 3) & 1, row = idx >> 4;
;     float x[8] = {bflo(w.x), bfhi(w.x), bflo(w.y), bfhi(w.y), bflo(w.z), bfhi(w.z), bflo(w.w), bfhi(w.w)};
;     float ssq = 0.f;
; #pragma unroll
;     for (int e = 0; e < 8; ++e) ssq += x[e] * x[e];
;     ssq += __shfl_xor(ssq, 1); ssq += __shfl_xor(ssq, 2); ssq += __shfl_xor(ssq, 4);
;     const float rh = __builtin_amdgcn_rsqf(ssq * (1.0f / 64.0f) + EPS);
;     const int t = row & (SEQ - 1), ir = (e8 < 4) ? (t >> 6) : (t & 63), f0 = 8 * (e8 & 1);
;     const f32x4 g0 = *(const f32x4*)(kg + e8 * 8), g1 = *(const f32x4*)(kg + e8 * 8 + 4);
;     const f32x4 c0 = *(const f32x4*)(rope + ir * 16 + f0), c1 = *(const f32x4*)(rope + ir * 16 + f0 + 4);
;     const f32x4 s0 = *(const f32x4*)(rope + 1024 + ir * 16 + f0), s1 = *(const f32x4*)(rope + 1024 + ir * 16 + f0 + 4);
;     const float sgn = (e8 & 2) ? 1.0f : -1.0f;
;     float o[8];
; #pragma unroll
;     for (int e = 0; e < 8; ++e) {
;         const float y = x[e] * rh * (e < 4 ? g0[e & 3] : g1[e & 3]);
;         const float other = __shfl_xor(y, 2);
;         o[e] = y * (e < 4 ? c0[e & 3] : c1[e & 3]) + sgn * other * (e < 4 ? s0[e & 3] : s1[e & 3]);
;     }
;     u32x4 r; r.x = cvt_pk_bf16(o[0], o[1]); r.y = cvt_pk_bf16(o[2], o[3]); r.z = cvt_pk_bf16(o[4], o[5]); r.w = cvt_pk_bf16(o[6], o[7]);
;     *(u32x4*)(P + (size_t)row * EVEN_IN + 1536 + hk * 64 + e8 * 8) = r;
	v_lshlrev_b32_e32 v200, 16, v52
	v_and_b32_e32 v201, 0xffff0000, v52
	v_lshlrev_b32_e32 v202, 16, v53
	v_and_b32_e32 v203, 0xffff0000, v53
	v_lshlrev_b32_e32 v204, 16, v54
	v_and_b32_e32 v205, 0xffff0000, v54
	v_lshlrev_b32_e32 v206, 16, v55
	v_and_b32_e32 v207, 0xffff0000, v55
	v_mul_f32_e32 v234, v200, v200
	v_fmac_f32_e32 v234, v201, v201
	v_fmac_f32_e32 v234, v202, v202
	v_fmac_f32_e32 v234, v203, v203
	v_fmac_f32_e32 v234, v204, v204
	v_fmac_f32_e32 v234, v205, v205
	v_fmac_f32_e32 v234, v206, v206
	v_fmac_f32_e32 v234, v207, v207
	s_nop 1
	v_add_f32_dpp v235, v234, v234 quad_perm:[1,0,3,2] row_mask:0xf bank_mask:0xf
	s_nop 1
	v_add_f32_dpp v234, v235, v235 quad_perm:[2,3,0,1] row_mask:0xf bank_mask:0xf
	s_nop 1
	v_add_f32_dpp v235, v234, v234 row_half_mirror row_mask:0xf bank_mask:0xf
	v_fmamk_f32 v235, v235, 0x3c800000, v217
	v_rsq_f32_e32 v235, v235
	s_nop 0
	v_mul_f32_e32 v200, v200, v235
	v_mul_f32_e32 v201, v201, v235
	v_mul_f32_e32 v202, v202, v235
	v_mul_f32_e32 v203, v203, v235
	v_mul_f32_e32 v204, v204, v235
	v_mul_f32_e32 v205, v205, v235
	v_mul_f32_e32 v206, v206, v235
	v_mul_f32_e32 v207, v207, v235
	v_mul_f32_e32 v200, v200, v40
	v_mul_f32_e32 v201, v201, v41
	v_mul_f32_e32 v202, v202, v42
	v_mul_f32_e32 v203, v203, v43
	v_mul_f32_e32 v204, v204, v44
	v_mul_f32_e32 v205, v205, v45
	v_mul_f32_e32 v206, v206, v46
	v_mul_f32_e32 v207, v207, v47
	s_nop 1
	v_mov_b32_dpp v208, v200 quad_perm:[2,3,0,1] row_mask:0xf bank_mask:0xf
	v_mov_b32_dpp v209, v201 quad_perm:[2,3,0,1] row_mask:0xf bank_mask:0xf
	v_mov_b32_dpp v210, v202 quad_perm:[2,3,0,1] row_mask:0xf bank_mask:0xf
	v_mov_b32_dpp v211, v203 quad_perm:[2,3,0,1] row_mask:0xf bank_mask:0xf
	v_mov_b32_dpp v212, v204 quad_perm:[2,3,0,1] row_mask:0xf bank_mask:0xf
	v_mov_b32_dpp v213, v205 quad_perm:[2,3,0,1] row_mask:0xf bank_mask:0xf
	v_mov_b32_dpp v214, v206 quad_perm:[2,3,0,1] row_mask:0xf bank_mask:0xf
	v_mov_b32_dpp v215, v207 quad_perm:[2,3,0,1] row_mask:0xf bank_mask:0xf
	v_mul_f32_e32 v208, v39, v208
	v_mul_f32_e32 v209, v39, v209
	v_mul_f32_e32 v210, v39, v210
	v_mul_f32_e32 v211, v39, v211
	v_mul_f32_e32 v212, v39, v212
	v_mul_f32_e32 v213, v39, v213
	v_mul_f32_e32 v214, v39, v214
	v_mul_f32_e32 v215, v39, v215
	v_mul_f32_e32 v208, v208, v104
	v_mul_f32_e32 v209, v209, v105
	v_mul_f32_e32 v210, v210, v106
	v_mul_f32_e32 v211, v211, v107
	v_mul_f32_e32 v212, v212, v108
	v_mul_f32_e32 v213, v213, v109
	v_mul_f32_e32 v214, v214, v110
	v_mul_f32_e32 v215, v215, v111
	v_fma_f32 v200, v200, v96, v208
	v_fma_f32 v201, v201, v97, v209
	v_fma_f32 v202, v202, v98, v210
	v_fma_f32 v203, v203, v99, v211
	v_fma_f32 v204, v204, v100, v212
	v_fma_f32 v205, v205, v101, v213
	v_fma_f32 v206, v206, v102, v214
	v_fma_f32 v207, v207, v103, v215
	v_cvt_pk_bf16_f32 v240, v200, v201
	v_cvt_pk_bf16_f32 v241, v202, v203
	v_cvt_pk_bf16_f32 v242, v204, v205
	v_cvt_pk_bf16_f32 v243, v206, v207
	v_add_u32_e32 v37, 0x24000, v37
	global_store_dwordx4 v37, v[240:243], s[0:1] offset:3072
	v_add_u32_e32 v34, 32, v34
	v_and_b32_e32 v35, 0xfff, v34
	v_lshrrev_b32_e32 v242, 6, v35
	v_and_b32_e32 v243, 63, v35
	v_cndmask_b32_e32 v242, v243, v242, vcc
	v_lshl_add_u32 v130, v242, 6, v38
	v_lshl_add_u64 v[244:245], s[8:9], 0, v[130:131]
	global_load_dwordx4 v[96:99], v[244:245], off
	global_load_dwordx4 v[100:103], v[244:245], off offset:16
	v_add_u32_e32 v130, 0x1000, v130
	v_lshl_add_u64 v[244:245], s[8:9], 0, v[130:131]
	global_load_dwordx4 v[104:107], v[244:245], off
	global_load_dwordx4 v[108:111], v[244:245], off offset:16
	s_waitcnt vmcnt(10)
	v_lshlrev_b32_e32 v200, 16, v56
	v_and_b32_e32 v201, 0xffff0000, v56
	v_lshlrev_b32_e32 v202, 16, v57
	v_and_b32_e32 v203, 0xffff0000, v57
	v_lshlrev_b32_e32 v204, 16, v58
	v_and_b32_e32 v205, 0xffff0000, v58
	v_lshlrev_b32_e32 v206, 16, v59
	v_and_b32_e32 v207, 0xffff0000, v59
	v_mul_f32_e32 v234, v200, v200
	v_fmac_f32_e32 v234, v201, v201
	v_fmac_f32_e32 v234, v202, v202
	v_fmac_f32_e32 v234, v203, v203
	v_fmac_f32_e32 v234, v204, v204
	v_fmac_f32_e32 v234, v205, v205
	v_fmac_f32_e32 v234, v206, v206
	v_fmac_f32_e32 v234, v207, v207
	s_nop 1
	v_add_f32_dpp v235, v234, v234 quad_perm:[1,0,3,2] row_mask:0xf bank_mask:0xf
	s_nop 1
	v_add_f32_dpp v234, v235, v235 quad_perm:[2,3,0,1] row_mask:0xf bank_mask:0xf
	s_nop 1
	v_add_f32_dpp v235, v234, v234 row_half_mirror row_mask:0xf bank_mask:0xf
	v_fmamk_f32 v235, v235, 0x3c800000, v217
	v_rsq_f32_e32 v235, v235
	s_nop 0
	v_mul_f32_e32 v200, v200, v235
	v_mul_f32_e32 v201, v201, v235
	v_mul_f32_e32 v202, v202, v235
	v_mul_f32_e32 v203, v203, v235
	v_mul_f32_e32 v204, v204, v235
	v_mul_f32_e32 v205, v205, v235
	v_mul_f32_e32 v206, v206, v235
	v_mul_f32_e32 v207, v207, v235
	v_mul_f32_e32 v200, v200, v40
	v_mul_f32_e32 v201, v201, v41
	v_mul_f32_e32 v202, v202, v42
	v_mul_f32_e32 v203, v203, v43
	v_mul_f32_e32 v204, v204, v44
	v_mul_f32_e32 v205, v205, v45
	v_mul_f32_e32 v206, v206, v46
	v_mul_f32_e32 v207, v207, v47
	s_nop 1
	v_mov_b32_dpp v208, v200 quad_perm:[2,3,0,1] row_mask:0xf bank_mask:0xf
	v_mov_b32_dpp v209, v201 quad_perm:[2,3,0,1] row_mask:0xf bank_mask:0xf
	v_mov_b32_dpp v210, v202 quad_perm:[2,3,0,1] row_mask:0xf bank_mask:0xf
	v_mov_b32_dpp v211, v203 quad_perm:[2,3,0,1] row_mask:0xf bank_mask:0xf
	v_mov_b32_dpp v212, v204 quad_perm:[2,3,0,1] row_mask:0xf bank_mask:0xf
	v_mov_b32_dpp v213, v205 quad_perm:[2,3,0,1] row_mask:0xf bank_mask:0xf
	v_mov_b32_dpp v214, v206 quad_perm:[2,3,0,1] row_mask:0xf bank_mask:0xf
	v_mov_b32_dpp v215, v207 quad_perm:[2,3,0,1] row_mask:0xf bank_mask:0xf
	v_mul_f32_e32 v208, v39, v208
	v_mul_f32_e32 v209, v39, v209
	v_mul_f32_e32 v210, v39, v210
	v_mul_f32_e32 v211, v39, v211
; __device__ __forceinline__ unsigned cvt_pk_bf16(float lo, float hi) { unsigned r; asm volatile("v_cvt_pk_bf16_f32 %0, %1, %2" : "=v"(r) : "v"(lo), "v"(hi)); return r; }
; __device__ __forceinline__ float bflo(unsigned w) { return __uint_as_float(w << 16); }
; __device__ __forceinline__ float bfhi(unsigned w) { return __uint_as_float(w & 0xffff0000u); }
; __device__ __forceinline__ void kprep_item(bf16_t* P, const float* kg, const float* rope, int idx, const u32x4 w) {
;     const int e8 = idx & 7, hk = (idx >> 3) & 1, row = idx >> 4;
;     float x[8] = {bflo(w.x), bfhi(w.x), bflo(w.y), bfhi(w.y), bflo(w.z), bfhi(w.z), bflo(w.w), bfhi(w.w)};
;     float ssq = 0.f;
; #pragma unroll
;     for (int e = 0; e < 8; ++e) ssq += x[e] * x[e];
;     ssq += __shfl_xor(ssq, 1); ssq += __shfl_xor(ssq, 2); ssq += __shfl_xor(ssq, 4);
;     const float rh = __builtin_amdgcn_rsqf(ssq * (1.0f / 64.0f) + EPS);
;     const int t = row & (SEQ - 1), ir = (e8 < 4) ? (t >> 6) : (t & 63), f0 = 8 * (e8 & 1);
;     const f32x4 g0 = *(const f32x4*)(kg + e8 * 8), g1 = *(const f32x4*)(kg + e8 * 8 + 4);
;     const f32x4 c0 = *(const f32x4*)(rope + ir * 16 + f0), c1 = *(const f32x4*)(rope + ir * 16 + f0 + 4);
;     const f32x4 s0 = *(const f32x4*)(rope + 1024 + ir * 16 + f0), s1 = *(const f32x4*)(rope + 1024 + ir * 16 + f0 + 4);
;     const float sgn = (e8 & 2) ? 1.0f : -1.0f;
;     float o[8];
; #pragma unroll
;     for (int e = 0; e < 8; ++e) {
;         const float y = x[e] * rh * (e < 4 ? g0[e & 3] : g1[e & 3]);
;         const float other = __shfl_xor(y, 2);
;         o[e] = y * (e < 4 ? c0[e & 3] : c1[e & 3]) + sgn * other * (e < 4 ? s0[e & 3] : s1[e & 3]);
;     }
;     u32x4 r; r.x = cvt_pk_bf16(o[0], o[1]); r.y = cvt_pk_bf16(o[2], o[3]); r.z = cvt_pk_bf16(o[4], o[5]); r.w = cvt_pk_bf16(o[6], o[7]);
;     *(u32x4*)(P + (size_t)row * EVEN_IN + 1536 + hk * 64 + e8 * 8) = r;
	v_mul_f32_e32 v212, v39, v212
	v_mul_f32_e32 v213, v39, v213
	v_mul_f32_e32 v214, v39, v214
	v_mul_f32_e32 v215, v39, v215
	v_mul_f32_e32 v208, v208, v122
	v_mul_f32_e32 v209, v209, v123
	v_mul_f32_e32 v210, v210, v124
	v_mul_f32_e32 v211, v211, v125
	v_mul_f32_e32 v212, v212, v126
	v_mul_f32_e32 v213, v213, v127
	v_mul_f32_e32 v214, v214, v128
	v_mul_f32_e32 v215, v215, v129
	v_fma_f32 v200, v200, v114, v208
	v_fma_f32 v201, v201, v115, v209
	v_fma_f32 v202, v202, v116, v210
	v_fma_f32 v203, v203, v117, v211
	v_fma_f32 v204, v204, v118, v212
	v_fma_f32 v205, v205, v119, v213
	v_fma_f32 v206, v206, v120, v214
	v_fma_f32 v207, v207, v121, v215
	v_cvt_pk_bf16_f32 v240, v200, v201
	v_cvt_pk_bf16_f32 v241, v202, v203
	v_cvt_pk_bf16_f32 v242, v204, v205
	v_cvt_pk_bf16_f32 v243, v206, v207
	v_add_u32_e32 v37, 0x24000, v37
	global_store_dwordx4 v37, v[240:243], s[0:1] offset:3072
	v_add_u32_e32 v34, 32, v34
	v_and_b32_e32 v35, 0xfff, v34
	v_lshrrev_b32_e32 v242, 6, v35
	v_and_b32_e32 v243, 63, v35
	v_cndmask_b32_e32 v242, v243, v242, vcc
	v_lshl_add_u32 v130, v242, 6, v38
	v_lshl_add_u64 v[244:245], s[8:9], 0, v[130:131]
	global_load_dwordx4 v[114:117], v[244:245], off
	global_load_dwordx4 v[118:121], v[244:245], off offset:16
	v_add_u32_e32 v130, 0x1000, v130
	v_lshl_add_u64 v[244:245], s[8:9], 0, v[130:131]
	global_load_dwordx4 v[122:125], v[244:245], off
	global_load_dwordx4 v[126:129], v[244:245], off offset:16
	s_waitcnt vmcnt(10)
	v_lshlrev_b32_e32 v200, 16, v60
	v_and_b32_e32 v201, 0xffff0000, v60
	v_lshlrev_b32_e32 v202, 16, v61
	v_and_b32_e32 v203, 0xffff0000, v61
	v_lshlrev_b32_e32 v204, 16, v62
	v_and_b32_e32 v205, 0xffff0000, v62
	v_lshlrev_b32_e32 v206, 16, v63
	v_and_b32_e32 v207, 0xffff0000, v63
	v_mul_f32_e32 v234, v200, v200
	v_fmac_f32_e32 v234, v201, v201
	v_fmac_f32_e32 v234, v202, v202
	v_fmac_f32_e32 v234, v203, v203
	v_fmac_f32_e32 v234, v204, v204
	v_fmac_f32_e32 v234, v205, v205
	v_fmac_f32_e32 v234, v206, v206
	v_fmac_f32_e32 v234, v207, v207
	s_nop 1
	v_add_f32_dpp v235, v234, v234 quad_perm:[1,0,3,2] row_mask:0xf bank_mask:0xf
	s_nop 1
	v_add_f32_dpp v234, v235, v235 quad_perm:[2,3,0,1] row_mask:0xf bank_mask:0xf
	s_nop 1
	v_add_f32_dpp v235, v234, v234 row_half_mirror row_mask:0xf bank_mask:0xf
	v_fmamk_f32 v235, v235, 0x3c800000, v217
	v_rsq_f32_e32 v235, v235
	s_nop 0
	v_mul_f32_e32 v200, v200, v235
	v_mul_f32_e32 v201, v201, v235
	v_mul_f32_e32 v202, v202, v235
	v_mul_f32_e32 v203, v203, v235
	v_mul_f32_e32 v204, v204, v235
	v_mul_f32_e32 v205, v205, v235
	v_mul_f32_e32 v206, v206, v235
	v_mul_f32_e32 v207, v207, v235
	v_mul_f32_e32 v200, v200, v40
	v_mul_f32_e32 v201, v201, v41
	v_mul_f32_e32 v202, v202, v42
	v_mul_f32_e32 v203, v203, v43
	v_mul_f32_e32 v204, v204, v44
	v_mul_f32_e32 v205, v205, v45
	v_mul_f32_e32 v206, v206, v46
	v_mul_f32_e32 v207, v207, v47
	s_nop 1
	v_mov_b32_dpp v208, v200 quad_perm:[2,3,0,1] row_mask:0xf bank_mask:0xf
	v_mov_b32_dpp v209, v201 quad_perm:[2,3,0,1] row_mask:0xf bank_mask:0xf
	v_mov_b32_dpp v210, v202 quad_perm:[2,3,0,1] row_mask:0xf bank_mask:0xf
	v_mov_b32_dpp v211, v203 quad_perm:[2,3,0,1] row_mask:0xf bank_mask:0xf
	v_mov_b32_dpp v212, v204 quad_perm:[2,3,0,1] row_mask:0xf bank_mask:0xf
	v_mov_b32_dpp v213, v205 quad_perm:[2,3,0,1] row_mask:0xf bank_mask:0xf
	v_mov_b32_dpp v214, v206 quad_perm:[2,3,0,1] row_mask:0xf bank_mask:0xf
	v_mov_b32_dpp v215, v207 quad_perm:[2,3,0,1] row_mask:0xf bank_mask:0xf
	v_mul_f32_e32 v208, v39, v208
	v_mul_f32_e32 v209, v39, v209
	v_mul_f32_e32 v210, v39, v210
	v_mul_f32_e32 v211, v39, v211
	v_mul_f32_e32 v212, v39, v212
	v_mul_f32_e32 v213, v39, v213
	v_mul_f32_e32 v214, v39, v214
	v_mul_f32_e32 v215, v39, v215
	v_mul_f32_e32 v208, v208, v88
	v_mul_f32_e32 v209, v209, v89
	v_mul_f32_e32 v210, v210, v90
	v_mul_f32_e32 v211, v211, v91
	v_mul_f32_e32 v212, v212, v92
	v_mul_f32_e32 v213, v213, v93
	v_mul_f32_e32 v214, v214, v94
	v_mul_f32_e32 v215, v215, v95
	v_fma_f32 v200, v200, v80, v208
	v_fma_f32 v201, v201, v81, v209
	v_fma_f32 v202, v202, v82, v210
	v_fma_f32 v203, v203, v83, v211
	v_fma_f32 v204, v204, v84, v212
	v_fma_f32 v205, v205, v85, v213
	v_fma_f32 v206, v206, v86, v214
	v_fma_f32 v207, v207, v87, v215
	v_cvt_pk_bf16_f32 v240, v200, v201
	v_cvt_pk_bf16_f32 v241, v202, v203
	v_cvt_pk_bf16_f32 v242, v204, v205
	v_cvt_pk_bf16_f32 v243, v206, v207
	v_add_u32_e32 v37, 0x24000, v37
	global_store_dwordx4 v37, v[240:243], s[0:1] offset:3072
	v_add_u32_e32 v34, 32, v34
	v_and_b32_e32 v35, 0xfff, v34
	v_lshrrev_b32_e32 v242, 6, v35
	v_and_b32_e32 v243, 63, v35
	v_cndmask_b32_e32 v242, v243, v242, vcc
	v_lshl_add_u32 v130, v242, 6, v38
	v_lshl_add_u64 v[244:245], s[8:9], 0, v[130:131]
	global_load_dwordx4 v[80:83], v[244:245], off
	global_load_dwordx4 v[84:87], v[244:245], off offset:16
	v_add_u32_e32 v130, 0x1000, v130
	v_lshl_add_u64 v[244:245], s[8:9], 0, v[130:131]
	global_load_dwordx4 v[88:91], v[244:245], off
	global_load_dwordx4 v[92:95], v[244:245], off offset:16
	s_waitcnt vmcnt(10)
; __device__ __forceinline__ unsigned cvt_pk_bf16(float lo, float hi) { unsigned r; asm volatile("v_cvt_pk_bf16_f32 %0, %1, %2" : "=v"(r) : "v"(lo), "v"(hi)); return r; }
; __device__ __forceinline__ float bflo(unsigned w) { return __uint_as_float(w << 16); }
; __device__ __forceinline__ float bfhi(unsigned w) { return __uint_as_float(w & 0xffff0000u); }
; __device__ __forceinline__ void kprep_item(bf16_t* P, const float* kg, const float* rope, int idx, const u32x4 w) {
;     const int e8 = idx & 7, hk = (idx >> 3) & 1, row = idx >> 4;
;     float x[8] = {bflo(w.x), bfhi(w.x), bflo(w.y), bfhi(w.y), bflo(w.z), bfhi(w.z), bflo(w.w), bfhi(w.w)};
;     float ssq = 0.f;
; #pragma unroll
;     for (int e = 0; e < 8; ++e) ssq += x[e] * x[e];
;     ssq += __shfl_xor(ssq, 1); ssq += __shfl_xor(ssq, 2); ssq += __shfl_xor(ssq, 4);
;     const float rh = __builtin_amdgcn_rsqf(ssq * (1.0f / 64.0f) + EPS);
;     const int t = row & (SEQ - 1), ir = (e8 < 4) ? (t >> 6) : (t & 63), f0 = 8 * (e8 & 1);
;     const f32x4 g0 = *(const f32x4*)(kg + e8 * 8), g1 = *(const f32x4*)(kg + e8 * 8 + 4);
;     const f32x4 c0 = *(const f32x4*)(rope + ir * 16 + f0), c1 = *(const f32x4*)(rope + ir * 16 + f0 + 4);
;     const f32x4 s0 = *(const f32x4*)(rope + 1024 + ir * 16 + f0), s1 = *(const f32x4*)(rope + 1024 + ir * 16 + f0 + 4);
;     const float sgn = (e8 & 2) ? 1.0f : -1.0f;
;     float o[8];
; #pragma unroll
;     for (int e = 0; e < 8; ++e) {
;         const float y = x[e] * rh * (e < 4 ? g0[e & 3] : g1[e & 3]);
;         const float other = __shfl_xor(y, 2);
;         o[e] = y * (e < 4 ? c0[e & 3] : c1[e & 3]) + sgn * other * (e < 4 ? s0[e & 3] : s1[e & 3]);
;     }
;     u32x4 r; r.x = cvt_pk_bf16(o[0], o[1]); r.y = cvt_pk_bf16(o[2], o[3]); r.z = cvt_pk_bf16(o[4], o[5]); r.w = cvt_pk_bf16(o[6], o[7]);
;     *(u32x4*)(P + (size_t)row * EVEN_IN + 1536 + hk * 64 + e8 * 8) = r;
	v_lshlrev_b32_e32 v200, 16, v64
	v_and_b32_e32 v201, 0xffff0000, v64
	v_lshlrev_b32_e32 v202, 16, v65
	v_and_b32_e32 v203, 0xffff0000, v65
	v_lshlrev_b32_e32 v204, 16, v66
	v_and_b32_e32 v205, 0xffff0000, v66
	v_lshlrev_b32_e32 v206, 16, v67
	v_and_b32_e32 v207, 0xffff0000, v67
	v_mul_f32_e32 v234, v200, v200
	v_fmac_f32_e32 v234, v201, v201
	v_fmac_f32_e32 v234, v202, v202
	v_fmac_f32_e32 v234, v203, v203
	v_fmac_f32_e32 v234, v204, v204
	v_fmac_f32_e32 v234, v205, v205
	v_fmac_f32_e32 v234, v206, v206
	v_fmac_f32_e32 v234, v207, v207
	s_nop 1
	v_add_f32_dpp v235, v234, v234 quad_perm:[1,0,3,2] row_mask:0xf bank_mask:0xf
	s_nop 1
	v_add_f32_dpp v234, v235, v235 quad_perm:[2,3,0,1] row_mask:0xf bank_mask:0xf
	s_nop 1
	v_add_f32_dpp v235, v234, v234 row_half_mirror row_mask:0xf bank_mask:0xf
	v_fmamk_f32 v235, v235, 0x3c800000, v217
	v_rsq_f32_e32 v235, v235
	s_nop 0
	v_mul_f32_e32 v200, v200, v235
	v_mul_f32_e32 v201, v201, v235
	v_mul_f32_e32 v202, v202, v235
	v_mul_f32_e32 v203, v203, v235
	v_mul_f32_e32 v204, v204, v235
	v_mul_f32_e32 v205, v205, v235
	v_mul_f32_e32 v206, v206, v235
	v_mul_f32_e32 v207, v207, v235
	v_mul_f32_e32 v200, v200, v40
	v_mul_f32_e32 v201, v201, v41
	v_mul_f32_e32 v202, v202, v42
	v_mul_f32_e32 v203, v203, v43
	v_mul_f32_e32 v204, v204, v44
	v_mul_f32_e32 v205, v205, v45
	v_mul_f32_e32 v206, v206, v46
	v_mul_f32_e32 v207, v207, v47
	s_nop 1
	v_mov_b32_dpp v208, v200 quad_perm:[2,3,0,1] row_mask:0xf bank_mask:0xf
	v_mov_b32_dpp v209, v201 quad_perm:[2,3,0,1] row_mask:0xf bank_mask:0xf
	v_mov_b32_dpp v210, v202 quad_perm:[2,3,0,1] row_mask:0xf bank_mask:0xf
	v_mov_b32_dpp v211, v203 quad_perm:[2,3,0,1] row_mask:0xf bank_mask:0xf
	v_mov_b32_dpp v212, v204 quad_perm:[2,3,0,1] row_mask:0xf bank_mask:0xf
	v_mov_b32_dpp v213, v205 quad_perm:[2,3,0,1] row_mask:0xf bank_mask:0xf
	v_mov_b32_dpp v214, v206 quad_perm:[2,3,0,1] row_mask:0xf bank_mask:0xf
	v_mov_b32_dpp v215, v207 quad_perm:[2,3,0,1] row_mask:0xf bank_mask:0xf
	v_mul_f32_e32 v208, v39, v208
	v_mul_f32_e32 v209, v39, v209
	v_mul_f32_e32 v210, v39, v210
	v_mul_f32_e32 v211, v39, v211
	v_mul_f32_e32 v212, v39, v212
	v_mul_f32_e32 v213, v39, v213
	v_mul_f32_e32 v214, v39, v214
	v_mul_f32_e32 v215, v39, v215
	v_mul_f32_e32 v208, v208, v104
	v_mul_f32_e32 v209, v209, v105
	v_mul_f32_e32 v210, v210, v106
	v_mul_f32_e32 v211, v211, v107
	v_mul_f32_e32 v212, v212, v108
	v_mul_f32_e32 v213, v213, v109
	v_mul_f32_e32 v214, v214, v110
	v_mul_f32_e32 v215, v215, v111
	v_fma_f32 v200, v200, v96, v208
	v_fma_f32 v201, v201, v97, v209
	v_fma_f32 v202, v202, v98, v210
	v_fma_f32 v203, v203, v99, v211
	v_fma_f32 v204, v204, v100, v212
	v_fma_f32 v205, v205, v101, v213
	v_fma_f32 v206, v206, v102, v214
	v_fma_f32 v207, v207, v103, v215
	v_cvt_pk_bf16_f32 v240, v200, v201
	v_cvt_pk_bf16_f32 v241, v202, v203
	v_cvt_pk_bf16_f32 v242, v204, v205
	v_cvt_pk_bf16_f32 v243, v206, v207
	v_add_u32_e32 v37, 0x24000, v37
	global_store_dwordx4 v37, v[240:243], s[0:1] offset:3072
	v_add_u32_e32 v34, 32, v34
	v_and_b32_e32 v35, 0xfff, v34
	v_lshrrev_b32_e32 v242, 6, v35
	v_and_b32_e32 v243, 63, v35
	v_cndmask_b32_e32 v242, v243, v242, vcc
	v_lshl_add_u32 v130, v242, 6, v38
	v_lshl_add_u64 v[244:245], s[8:9], 0, v[130:131]
	global_load_dwordx4 v[96:99], v[244:245], off
	global_load_dwordx4 v[100:103], v[244:245], off offset:16
	v_add_u32_e32 v130, 0x1000, v130
	v_lshl_add_u64 v[244:245], s[8:9], 0, v[130:131]
	global_load_dwordx4 v[104:107], v[244:245], off
	global_load_dwordx4 v[108:111], v[244:245], off offset:16
	s_waitcnt vmcnt(10)
	v_lshlrev_b32_e32 v200, 16, v68
	v_and_b32_e32 v201, 0xffff0000, v68
	v_lshlrev_b32_e32 v202, 16, v69
	v_and_b32_e32 v203, 0xffff0000, v69
	v_lshlrev_b32_e32 v204, 16, v70
	v_and_b32_e32 v205, 0xffff0000, v70
	v_lshlrev_b32_e32 v206, 16, v71
	v_and_b32_e32 v207, 0xffff0000, v71
	v_mul_f32_e32 v234, v200, v200
	v_fmac_f32_e32 v234, v201, v201
	v_fmac_f32_e32 v234, v202, v202
	v_fmac_f32_e32 v234, v203, v203
	v_fmac_f32_e32 v234, v204, v204
	v_fmac_f32_e32 v234, v205, v205
	v_fmac_f32_e32 v234, v206, v206
	v_fmac_f32_e32 v234, v207, v207
	s_nop 1
	v_add_f32_dpp v235, v234, v234 quad_perm:[1,0,3,2] row_mask:0xf bank_mask:0xf
	s_nop 1
	v_add_f32_dpp v234, v235, v235 quad_perm:[2,3,0,1] row_mask:0xf bank_mask:0xf
	s_nop 1
	v_add_f32_dpp v235, v234, v234 row_half_mirror row_mask:0xf bank_mask:0xf
	v_fmamk_f32 v235, v235, 0x3c800000, v217
	v_rsq_f32_e32 v235, v235
	s_nop 0
	v_mul_f32_e32 v200, v200, v235
	v_mul_f32_e32 v201, v201, v235
	v_mul_f32_e32 v202, v202, v235
	v_mul_f32_e32 v203, v203, v235
	v_mul_f32_e32 v204, v204, v235
	v_mul_f32_e32 v205, v205, v235
	v_mul_f32_e32 v206, v206, v235
	v_mul_f32_e32 v207, v207, v235
	v_mul_f32_e32 v200, v200, v40
	v_mul_f32_e32 v201, v201, v41
	v_mul_f32_e32 v202, v202, v42
	v_mul_f32_e32 v203, v203, v43
	v_mul_f32_e32 v204, v204, v44
	v_mul_f32_e32 v205, v205, v45
	v_mul_f32_e32 v206, v206, v46
	v_mul_f32_e32 v207, v207, v47
	s_nop 1
	v_mov_b32_dpp v208, v200 quad_perm:[2,3,0,1] row_mask:0xf bank_mask:0xf
	v_mov_b32_dpp v209, v201 quad_perm:[2,3,0,1] row_mask:0xf bank_mask:0xf
	v_mov_b32_dpp v210, v202 quad_perm:[2,3,0,1] row_mask:0xf bank_mask:0xf
	v_mov_b32_dpp v211, v203 quad_perm:[2,3,0,1] row_mask:0xf bank_mask:0xf
	v_mov_b32_dpp v212, v204 quad_perm:[2,3,0,1] row_mask:0xf bank_mask:0xf
	v_mov_b32_dpp v213, v205 quad_perm:[2,3,0,1] row_mask:0xf bank_mask:0xf
	v_mov_b32_dpp v214, v206 quad_perm:[2,3,0,1] row_mask:0xf bank_mask:0xf
	v_mov_b32_dpp v215, v207 quad_perm:[2,3,0,1] row_mask:0xf bank_mask:0xf
	v_mul_f32_e32 v208, v39, v208
	v_mul_f32_e32 v209, v39, v209
	v_mul_f32_e32 v210, v39, v210
	v_mul_f32_e32 v211, v39, v211
	v_mul_f32_e32 v212, v39, v212
	v_mul_f32_e32 v213, v39, v213
	v_mul_f32_e32 v214, v39, v214
	v_mul_f32_e32 v215, v39, v215
	v_mul_f32_e32 v208, v208, v122
	v_mul_f32_e32 v209, v209, v123
	v_mul_f32_e32 v210, v210, v124
	v_mul_f32_e32 v211, v211, v125
	v_mul_f32_e32 v212, v212, v126
	v_mul_f32_e32 v213, v213, v127
	v_mul_f32_e32 v214, v214, v128
	v_mul_f32_e32 v215, v215, v129
	v_fma_f32 v200, v200, v114, v208
	v_fma_f32 v201, v201, v115, v209
	v_fma_f32 v202, v202, v116, v210
	v_fma_f32 v203, v203, v117, v211
	v_fma_f32 v204, v204, v118, v212
	v_fma_f32 v205, v205, v119, v213
	v_fma_f32 v206, v206, v120, v214
	v_fma_f32 v207, v207, v121, v215
	v_cvt_pk_bf16_f32 v240, v200, v201
	v_cvt_pk_bf16_f32 v241, v202, v203
	v_cvt_pk_bf16_f32 v242, v204, v205
	v_cvt_pk_bf16_f32 v243, v206, v207
	v_add_u32_e32 v37, 0x24000, v37
	global_store_dwordx4 v37, v[240:243], s[0:1] offset:3072
	s_waitcnt vmcnt(6)
; __device__ __forceinline__ unsigned cvt_pk_bf16(float lo, float hi) { unsigned r; asm volatile("v_cvt_pk_bf16_f32 %0, %1, %2" : "=v"(r) : "v"(lo), "v"(hi)); return r; }
; __device__ __forceinline__ float bflo(unsigned w) { return __uint_as_float(w << 16); }
; __device__ __forceinline__ float bfhi(unsigned w) { return __uint_as_float(w & 0xffff0000u); }
; __device__ __forceinline__ void kprep_item(bf16_t* P, const float* kg, const float* rope, int idx, const u32x4 w) {
;     ...
;     float x[8] = {bflo(w.x), bfhi(w.x), bflo(w.y), bfhi(w.y), bflo(w.z), bfhi(w.z), bflo(w.w), bfhi(w.w)};
;     float ssq = 0.f;
; #pragma unroll
;     for (int e = 0; e < 8; ++e) ssq += x[e] * x[e];
;     ssq += __shfl_xor(ssq, 1); ssq += __shfl_xor(ssq, 2); ssq += __shfl_xor(ssq, 4);
;     const float rh = __builtin_amdgcn_rsqf(ssq * (1.0f / 64.0f) + EPS);
;     const int t = row & (SEQ - 1), ir = (e8 < 4) ? (t >> 6) : (t & 63), f0 = 8 * (e8 & 1);
;     const f32x4 g0 = *(const f32x4*)(kg + e8 * 8), g1 = *(const f32x4*)(kg + e8 * 8 + 4);
;     const f32x4 c0 = *(const f32x4*)(rope + ir * 16 + f0), c1 = *(const f32x4*)(rope + ir * 16 + f0 + 4);
;     const f32x4 s0 = *(const f32x4*)(rope + 1024 + ir * 16 + f0), s1 = *(const f32x4*)(rope + 1024 + ir * 16 + f0 + 4);
;     const float sgn = (e8 & 2) ? 1.0f : -1.0f;
;     float o[8];
; #pragma unroll
;     for (int e = 0; e < 8; ++e) {
;         const float y = x[e] * rh * (e < 4 ? g0[e & 3] : g1[e & 3]);
;         const float other = __shfl_xor(y, 2);
;         o[e] = y * (e < 4 ? c0[e & 3] : c1[e & 3]) + sgn * other * (e < 4 ? s0[e & 3] : s1[e & 3]);
;     }
;     u32x4 r; r.x = cvt_pk_bf16(o[0], o[1]); r.y = cvt_pk_bf16(o[2], o[3]); r.z = cvt_pk_bf16(o[4], o[5]); r.w = cvt_pk_bf16(o[6], o[7]);
;     *(u32x4*)(P + (size_t)row * EVEN_IN + 1536 + hk * 64 + e8 * 8) = r;
	v_lshlrev_b32_e32 v200, 16, v72
	v_and_b32_e32 v201, 0xffff0000, v72
	v_lshlrev_b32_e32 v202, 16, v73
	v_and_b32_e32 v203, 0xffff0000, v73
	v_lshlrev_b32_e32 v204, 16, v74
	v_and_b32_e32 v205, 0xffff0000, v74
	v_lshlrev_b32_e32 v206, 16, v75
	v_and_b32_e32 v207, 0xffff0000, v75
	v_mul_f32_e32 v234, v200, v200
	v_fmac_f32_e32 v234, v201, v201
	v_fmac_f32_e32 v234, v202, v202
	v_fmac_f32_e32 v234, v203, v203
	v_fmac_f32_e32 v234, v204, v204
	v_fmac_f32_e32 v234, v205, v205
	v_fmac_f32_e32 v234, v206, v206
	v_fmac_f32_e32 v234, v207, v207
	s_nop 1
	v_add_f32_dpp v235, v234, v234 quad_perm:[1,0,3,2] row_mask:0xf bank_mask:0xf
	s_nop 1
	v_add_f32_dpp v234, v235, v235 quad_perm:[2,3,0,1] row_mask:0xf bank_mask:0xf
	s_nop 1
	v_add_f32_dpp v235, v234, v234 row_half_mirror row_mask:0xf bank_mask:0xf
	v_fmamk_f32 v235, v235, 0x3c800000, v217
	v_rsq_f32_e32 v235, v235
	s_nop 0
	v_mul_f32_e32 v200, v200, v235
	v_mul_f32_e32 v201, v201, v235
	v_mul_f32_e32 v202, v202, v235
	v_mul_f32_e32 v203, v203, v235
	v_mul_f32_e32 v204, v204, v235
	v_mul_f32_e32 v205, v205, v235
	v_mul_f32_e32 v206, v206, v235
	v_mul_f32_e32 v207, v207, v235
	v_mul_f32_e32 v200, v200, v40
	v_mul_f32_e32 v201, v201, v41
	v_mul_f32_e32 v202, v202, v42
	v_mul_f32_e32 v203, v203, v43
	v_mul_f32_e32 v204, v204, v44
	v_mul_f32_e32 v205, v205, v45
	v_mul_f32_e32 v206, v206, v46
	v_mul_f32_e32 v207, v207, v47
	s_nop 1
	v_mov_b32_dpp v208, v200 quad_perm:[2,3,0,1] row_mask:0xf bank_mask:0xf
	v_mov_b32_dpp v209, v201 quad_perm:[2,3,0,1] row_mask:0xf bank_mask:0xf
	v_mov_b32_dpp v210, v202 quad_perm:[2,3,0,1] row_mask:0xf bank_mask:0xf
	v_mov_b32_dpp v211, v203 quad_perm:[2,3,0,1] row_mask:0xf bank_mask:0xf
	v_mov_b32_dpp v212, v204 quad_perm:[2,3,0,1] row_mask:0xf bank_mask:0xf
	v_mov_b32_dpp v213, v205 quad_perm:[2,3,0,1] row_mask:0xf bank_mask:0xf
	v_mov_b32_dpp v214, v206 quad_perm:[2,3,0,1] row_mask:0xf bank_mask:0xf
	v_mov_b32_dpp v215, v207 quad_perm:[2,3,0,1] row_mask:0xf bank_mask:0xf
	v_mul_f32_e32 v208, v39, v208
	v_mul_f32_e32 v209, v39, v209
	v_mul_f32_e32 v210, v39, v210
	v_mul_f32_e32 v211, v39, v211
	v_mul_f32_e32 v212, v39, v212
	v_mul_f32_e32 v213, v39, v213
	v_mul_f32_e32 v214, v39, v214
	v_mul_f32_e32 v215, v39, v215
	v_mul_f32_e32 v208, v208, v88
	v_mul_f32_e32 v209, v209, v89
	v_mul_f32_e32 v210, v210, v90
	v_mul_f32_e32 v211, v211, v91
	v_mul_f32_e32 v212, v212, v92
	v_mul_f32_e32 v213, v213, v93
	v_mul_f32_e32 v214, v214, v94
	v_mul_f32_e32 v215, v215, v95
	v_fma_f32 v200, v200, v80, v208
	v_fma_f32 v201, v201, v81, v209
	v_fma_f32 v202, v202, v82, v210
	v_fma_f32 v203, v203, v83, v211
	v_fma_f32 v204, v204, v84, v212
	v_fma_f32 v205, v205, v85, v213
	v_fma_f32 v206, v206, v86, v214
	v_fma_f32 v207, v207, v87, v215
	v_cvt_pk_bf16_f32 v240, v200, v201
	v_cvt_pk_bf16_f32 v241, v202, v203
	v_cvt_pk_bf16_f32 v242, v204, v205
	v_cvt_pk_bf16_f32 v243, v206, v207
	v_add_u32_e32 v37, 0x24000, v37
	global_store_dwordx4 v37, v[240:243], s[0:1] offset:3072
	s_waitcnt vmcnt(2)
	v_lshlrev_b32_e32 v200, 16, v76
	v_and_b32_e32 v201, 0xffff0000, v76
	v_lshlrev_b32_e32 v202, 16, v77
	v_and_b32_e32 v203, 0xffff0000, v77
	v_lshlrev_b32_e32 v204, 16, v78
	v_and_b32_e32 v205, 0xffff0000, v78
	v_lshlrev_b32_e32 v206, 16, v79
	v_and_b32_e32 v207, 0xffff0000, v79
	v_mul_f32_e32 v234, v200, v200
	v_fmac_f32_e32 v234, v201, v201
	v_fmac_f32_e32 v234, v202, v202
	v_fmac_f32_e32 v234, v203, v203
	v_fmac_f32_e32 v234, v204, v204
	v_fmac_f32_e32 v234, v205, v205
	v_fmac_f32_e32 v234, v206, v206
	v_fmac_f32_e32 v234, v207, v207
	s_nop 1
	v_add_f32_dpp v235, v234, v234 quad_perm:[1,0,3,2] row_mask:0xf bank_mask:0xf
	s_nop 1
	v_add_f32_dpp v234, v235, v235 quad_perm:[2,3,0,1] row_mask:0xf bank_mask:0xf
	s_nop 1
	v_add_f32_dpp v235, v234, v234 row_half_mirror row_mask:0xf bank_mask:0xf
	v_fmamk_f32 v235, v235, 0x3c800000, v217
	v_rsq_f32_e32 v235, v235
	s_nop 0
	v_mul_f32_e32 v200, v200, v235
	v_mul_f32_e32 v201, v201, v235
	v_mul_f32_e32 v202, v202, v235
	v_mul_f32_e32 v203, v203, v235
	v_mul_f32_e32 v204, v204, v235
	v_mul_f32_e32 v205, v205, v235
	v_mul_f32_e32 v206, v206, v235
	v_mul_f32_e32 v207, v207, v235
	v_mul_f32_e32 v200, v200, v40
	v_mul_f32_e32 v201, v201, v41
	v_mul_f32_e32 v202, v202, v42
	v_mul_f32_e32 v203, v203, v43
	v_mul_f32_e32 v204, v204, v44
	v_mul_f32_e32 v205, v205, v45
	v_mul_f32_e32 v206, v206, v46
	v_mul_f32_e32 v207, v207, v47
	s_nop 1
	v_mov_b32_dpp v208, v200 quad_perm:[2,3,0,1] row_mask:0xf bank_mask:0xf
	v_mov_b32_dpp v209, v201 quad_perm:[2,3,0,1] row_mask:0xf bank_mask:0xf
	v_mov_b32_dpp v210, v202 quad_perm:[2,3,0,1] row_mask:0xf bank_mask:0xf
	v_mov_b32_dpp v211, v203 quad_perm:[2,3,0,1] row_mask:0xf bank_mask:0xf
	v_mov_b32_dpp v212, v204 quad_perm:[2,3,0,1] row_mask:0xf bank_mask:0xf
	v_mov_b32_dpp v213, v205 quad_perm:[2,3,0,1] row_mask:0xf bank_mask:0xf
	v_mov_b32_dpp v214, v206 quad_perm:[2,3,0,1] row_mask:0xf bank_mask:0xf
	v_mov_b32_dpp v215, v207 quad_perm:[2,3,0,1] row_mask:0xf bank_mask:0xf
	v_mul_f32_e32 v208, v39, v208
	v_mul_f32_e32 v209, v39, v209
	v_mul_f32_e32 v210, v39, v210
	v_mul_f32_e32 v211, v39, v211
	v_mul_f32_e32 v212, v39, v212
	v_mul_f32_e32 v213, v39, v213
	v_mul_f32_e32 v214, v39, v214
	v_mul_f32_e32 v215, v39, v215
	v_mul_f32_e32 v208, v208, v104
	v_mul_f32_e32 v209, v209, v105
	v_mul_f32_e32 v210, v210, v106
	v_mul_f32_e32 v211, v211, v107
	v_mul_f32_e32 v212, v212, v108
	v_mul_f32_e32 v213, v213, v109
	v_mul_f32_e32 v214, v214, v110
	v_mul_f32_e32 v215, v215, v111
	v_fma_f32 v200, v200, v96, v208
	v_fma_f32 v201, v201, v97, v209
	v_fma_f32 v202, v202, v98, v210
	v_fma_f32 v203, v203, v99, v211
	v_fma_f32 v204, v204, v100, v212
	v_fma_f32 v205, v205, v101, v213
	v_fma_f32 v206, v206, v102, v214
	v_fma_f32 v207, v207, v103, v215
	v_cvt_pk_bf16_f32 v240, v200, v201
	v_cvt_pk_bf16_f32 v241, v202, v203
	v_cvt_pk_bf16_f32 v242, v204, v205
	v_cvt_pk_bf16_f32 v243, v206, v207
	v_add_u32_e32 v37, 0x24000, v37
	global_store_dwordx4 v37, v[240:243], s[0:1] offset:3072
	v_readlane_b32 s13, v255, 49
	s_and_b64 vcc, exec, s[42:43]
